# phase-0 weight transposes: 16 LDS reads per item issued together; mix-GEMM gate hook: first gate-load wait moved behind the remaining loads
# baseline (speedup 1.0000x reference)
; #define LAS __attribute__((address_space(3)))
; __device__ __forceinline__ unsigned cvt_pk_bf16(float lo, float hi) { unsigned r; asm volatile("v_cvt_pk_bf16_f32 %0, %1, %2" : "=v"(r) : "v"(lo), "v"(hi)); return r; }
; __device__ __forceinline__ void p0_transpose_item(const float* W, int N, bf16_t* WT, int ldt, int coff, LAS float* scr, int item, int lane) {
;     const int nblk = N / 32, kb = item / nblk, nb = item % nblk, k0 = 64 * kb, n0 = 32 * nb;
;     { f32x4 v[8];
; #pragma unroll
;       for (int i = 0; i < 8; ++i) v[i] = __builtin_nontemporal_load((const f32x4*)(W + (size_t)(k0 + 8 * i + (lane >> 3)) * N + n0 + 4 * (lane & 7)));
; #pragma unroll
;       for (int i = 0; i < 8; ++i) { LAS float* d = scr + (8 * i + (lane >> 3)) * 33 + 4 * (lane & 7); d[0] = v[i].x; d[1] = v[i].y; d[2] = v[i].z; d[3] = v[i].w; } }
;     asm volatile("s_waitcnt lgkmcnt(0)" ::: "memory");
;     const int c = lane & 7;
; #pragma unroll
;     for (int j = 0; j < 4; ++j) { const int n = (lane >> 3) + 8 * j; const LAS float* s = scr + (8 * c) * 33 + n;
;         u32x4 o; o.x = cvt_pk_bf16(s[0 * 33], s[1 * 33]); o.y = cvt_pk_bf16(s[2 * 33], s[3 * 33]); o.z = cvt_pk_bf16(s[4 * 33], s[5 * 33]); o.w = cvt_pk_bf16(s[6 * 33], s[7 * 33]);
;         *(u32x4*)(WT + (size_t)(n0 + n) * ldt + coff + k0 + 8 * c) = o; }
;     asm volatile("s_waitcnt lgkmcnt(0)" ::: "memory");
; }
.LBB0_9:
	s_mul_hi_i32 s10, s0, 0x78787879
	s_lshr_b32 s11, s10, 31
	s_ashr_i32 s10, s10, 7
	s_add_i32 s11, s10, s11
	s_lshl_b32 s10, s11, 6
	s_mulk_i32 s11, 0xde00
	s_add_i32 s12, s1, s11
	v_or_b32_e32 v26, s10, v1
	s_ashr_i32 s13, s12, 31
	v_or_b32_e32 v28, 8, v26
	v_or_b32_e32 v30, 16, v26
	v_or_b32_e32 v31, 24, v26
	v_or_b32_e32 v34, 32, v26
	v_or_b32_e32 v35, 40, v26
	v_or_b32_e32 v38, 48, v26
	v_or_b32_e32 v39, 56, v26
	v_lshl_add_u64 v[24:25], s[12:13], 2, v[6:7]
	v_mad_i64_i32 v[26:27], s[14:15], v26, s3, v[24:25]
	v_mad_i64_i32 v[28:29], s[14:15], v28, s3, v[24:25]
	v_mad_i64_i32 v[32:33], s[14:15], v30, s3, v[24:25]
	v_mad_i64_i32 v[36:37], s[14:15], v31, s3, v[24:25]
	v_mad_i64_i32 v[40:41], s[14:15], v34, s3, v[24:25]
	v_mad_i64_i32 v[44:45], s[14:15], v35, s3, v[24:25]
	v_mad_i64_i32 v[48:49], s[14:15], v38, s3, v[24:25]
	v_mad_i64_i32 v[52:53], s[14:15], v39, s3, v[24:25]
	global_load_dwordx4 v[24:27], v[26:27], off nt
	s_nop 0
	global_load_dwordx4 v[28:31], v[28:29], off nt
	s_nop 0
	global_load_dwordx4 v[32:35], v[32:33], off nt
	s_nop 0
	global_load_dwordx4 v[36:39], v[36:37], off nt
	s_nop 0
	global_load_dwordx4 v[40:43], v[40:41], off nt
	s_nop 0
	global_load_dwordx4 v[44:47], v[44:45], off nt
	s_nop 0
	global_load_dwordx4 v[48:51], v[48:49], off nt
	s_nop 0
	global_load_dwordx4 v[52:55], v[52:53], off nt
	v_add_u32_e32 v58, s12, v1
	s_ashr_i32 s11, s10, 31
	v_ashrrev_i32_e32 v59, 31, v58
	v_lshl_add_u64 v[56:57], s[10:11], 1, v[8:9]
	v_lshlrev_b64 v[64:65], 12, v[58:59]
	v_add_u32_e32 v60, 8, v58
	v_lshl_add_u64 v[64:65], v[56:57], 0, v[64:65]
	v_ashrrev_i32_e32 v61, 31, v60
	v_lshlrev_b64 v[60:61], 12, v[60:61]
	v_add_u32_e32 v62, 16, v58
	v_lshl_add_u64 v[60:61], v[56:57], 0, v[60:61]
	v_ashrrev_i32_e32 v63, 31, v62
	v_lshlrev_b64 v[62:63], 12, v[62:63]
	v_lshl_add_u64 v[62:63], v[56:57], 0, v[62:63]
	s_add_i32 s0, s0, s94
	s_add_i32 s1, s1, s2
	s_cmpk_gt_i32 s0, 0x21ff
	s_waitcnt vmcnt(7)
	ds_write2_b32 v17, v24, v25 offset1:1
	ds_write2_b32 v17, v26, v27 offset0:2 offset1:3
	s_waitcnt vmcnt(6)
	ds_write2_b32 v3, v28, v29 offset1:1
	ds_write2_b32 v5, v30, v31 offset1:1
	s_waitcnt vmcnt(5)
	ds_write2_b32 v10, v32, v33 offset1:1
	ds_write2_b32 v11, v34, v35 offset1:1
	s_waitcnt vmcnt(4)
	ds_write2_b32 v12, v36, v37 offset1:1
	ds_write2_b32 v13, v38, v39 offset1:1
	s_waitcnt vmcnt(3)
	ds_write2_b32 v14, v40, v41 offset1:1
	ds_write2_b32 v15, v42, v43 offset1:1
	s_waitcnt vmcnt(2)
	ds_write2_b32 v18, v44, v45 offset1:1
	ds_write2_b32 v19, v46, v47 offset1:1
	s_waitcnt vmcnt(1)
	ds_write2_b32 v20, v48, v49 offset1:1
	ds_write2_b32 v21, v50, v51 offset1:1
	s_waitcnt vmcnt(0)
	ds_write2_b32 v22, v52, v53 offset1:1
	ds_write2_b32 v23, v54, v55 offset1:1
	s_waitcnt lgkmcnt(0)
	ds_read2_b32 v[92:93], v16 offset1:33
	ds_read2_b32 v[94:95], v16 offset0:66 offset1:99
	ds_read2_b32 v[96:97], v16 offset0:132 offset1:165
	ds_read2_b32 v[98:99], v16 offset0:198 offset1:231
	ds_read2_b32 v[100:101], v16 offset0:8 offset1:41
	ds_read2_b32 v[102:103], v16 offset0:74 offset1:107
	ds_read2_b32 v[104:105], v16 offset0:140 offset1:173
	ds_read2_b32 v[106:107], v16 offset0:206 offset1:239
	ds_read2_b32 v[108:109], v16 offset0:16 offset1:49
	ds_read2_b32 v[110:111], v16 offset0:82 offset1:115
	ds_read2_b32 v[112:113], v16 offset0:148 offset1:181
	ds_read2_b32 v[114:115], v16 offset0:214 offset1:247
	ds_read2_b32 v[116:117], v16 offset0:24 offset1:57
	ds_read2_b32 v[118:119], v16 offset0:90 offset1:123
	ds_read2_b32 v[120:121], v16 offset0:156 offset1:189
	ds_read2_b32 v[122:123], v16 offset0:222 offset1:255
	s_waitcnt lgkmcnt(0)
	s_nop 0
	v_cvt_pk_bf16_f32 v24, v92, v93
	s_nop 0
	v_cvt_pk_bf16_f32 v25, v94, v95
	s_nop 0
	v_cvt_pk_bf16_f32 v26, v96, v97
	s_nop 0
	v_cvt_pk_bf16_f32 v27, v98, v99
	global_store_dwordx4 v[64:65], v[24:27], off
	v_add_u32_e32 v30, 24, v58
	v_ashrrev_i32_e32 v31, 31, v30
	s_nop 0
	v_cvt_pk_bf16_f32 v24, v100, v101
	s_nop 0
	v_cvt_pk_bf16_f32 v25, v102, v103
	s_nop 0
	v_cvt_pk_bf16_f32 v26, v104, v105
	s_nop 0
	v_cvt_pk_bf16_f32 v27, v106, v107
	global_store_dwordx4 v[60:61], v[24:27], off
	v_lshlrev_b64 v[30:31], 12, v[30:31]
	v_lshl_add_u64 v[30:31], v[56:57], 0, v[30:31]
	s_nop 0
	v_cvt_pk_bf16_f32 v24, v108, v109
	s_nop 0
	v_cvt_pk_bf16_f32 v25, v110, v111
	s_nop 0
	v_cvt_pk_bf16_f32 v26, v112, v113
	s_nop 0
	v_cvt_pk_bf16_f32 v27, v114, v115
	global_store_dwordx4 v[62:63], v[24:27], off
	s_nop 0
	s_nop 0
	v_cvt_pk_bf16_f32 v24, v116, v117
	s_nop 0
	v_cvt_pk_bf16_f32 v25, v118, v119
	s_nop 0
	v_cvt_pk_bf16_f32 v26, v120, v121
	s_nop 0
	v_cvt_pk_bf16_f32 v27, v122, v123
	global_store_dwordx4 v[30:31], v[24:27], off
	s_waitcnt lgkmcnt(0)
	s_cbranch_scc0 .LBB0_9

; #define LAS __attribute__((address_space(3)))
; __device__ __forceinline__ unsigned cvt_pk_bf16(float lo, float hi) { unsigned r; asm volatile("v_cvt_pk_bf16_f32 %0, %1, %2" : "=v"(r) : "v"(lo), "v"(hi)); return r; }
; __device__ __forceinline__ void p0_transpose_item(const float* W, int N, bf16_t* WT, int ldt, int coff, LAS float* scr, int item, int lane) {
;     const int nblk = N / 32, kb = item / nblk, nb = item % nblk, k0 = 64 * kb, n0 = 32 * nb;
;     { f32x4 v[8];
; #pragma unroll
;       for (int i = 0; i < 8; ++i) v[i] = __builtin_nontemporal_load((const f32x4*)(W + (size_t)(k0 + 8 * i + (lane >> 3)) * N + n0 + 4 * (lane & 7)));
; #pragma unroll
;       for (int i = 0; i < 8; ++i) { LAS float* d = scr + (8 * i + (lane >> 3)) * 33 + 4 * (lane & 7); d[0] = v[i].x; d[1] = v[i].y; d[2] = v[i].z; d[3] = v[i].w; } }
;     asm volatile("s_waitcnt lgkmcnt(0)" ::: "memory");
;     const int c = lane & 7;
; #pragma unroll
;     for (int j = 0; j < 4; ++j) { const int n = (lane >> 3) + 8 * j; const LAS float* s = scr + (8 * c) * 33 + n;
;         u32x4 o; o.x = cvt_pk_bf16(s[0 * 33], s[1 * 33]); o.y = cvt_pk_bf16(s[2 * 33], s[3 * 33]); o.z = cvt_pk_bf16(s[4 * 33], s[5 * 33]); o.w = cvt_pk_bf16(s[6 * 33], s[7 * 33]);
;         *(u32x4*)(WT + (size_t)(n0 + n) * ldt + coff + k0 + 8 * c) = o; }
;     asm volatile("s_waitcnt lgkmcnt(0)" ::: "memory");
; }
.LBB0_12:
	s_mul_hi_i32 s11, s1, 0x2aaaaaab
	s_lshr_b32 s12, s11, 31
	s_ashr_i32 s11, s11, 5
	s_add_i32 s11, s11, s12
	s_lshl_b32 s12, s11, 6
	s_mulk_i32 s11, 0xe800
	s_add_i32 s14, s2, s11
	v_or_b32_e32 v26, s12, v1
	s_ashr_i32 s15, s14, 31
	v_or_b32_e32 v28, 8, v26
	v_or_b32_e32 v30, 16, v26
	v_or_b32_e32 v31, 24, v26
	v_or_b32_e32 v34, 32, v26
	v_or_b32_e32 v35, 40, v26
	v_or_b32_e32 v38, 48, v26
	v_or_b32_e32 v39, 56, v26
	v_lshl_add_u64 v[24:25], s[14:15], 2, v[6:7]
	v_mad_i64_i32 v[26:27], s[16:17], v26, s10, v[24:25]
	v_mad_i64_i32 v[28:29], s[16:17], v28, s10, v[24:25]
	v_mad_i64_i32 v[32:33], s[16:17], v30, s10, v[24:25]
	v_mad_i64_i32 v[36:37], s[16:17], v31, s10, v[24:25]
	v_mad_i64_i32 v[40:41], s[16:17], v34, s10, v[24:25]
	v_mad_i64_i32 v[44:45], s[16:17], v35, s10, v[24:25]
	v_mad_i64_i32 v[48:49], s[16:17], v38, s10, v[24:25]
	v_mad_i64_i32 v[52:53], s[16:17], v39, s10, v[24:25]
	global_load_dwordx4 v[24:27], v[26:27], off nt
	s_nop 0
	global_load_dwordx4 v[28:31], v[28:29], off nt
	s_nop 0
	global_load_dwordx4 v[32:35], v[32:33], off nt
	s_nop 0
	global_load_dwordx4 v[36:39], v[36:37], off nt
	s_nop 0
	global_load_dwordx4 v[40:43], v[40:41], off nt
	s_nop 0
	global_load_dwordx4 v[44:47], v[44:45], off nt
	s_nop 0
	global_load_dwordx4 v[48:51], v[48:49], off nt
	s_nop 0
	global_load_dwordx4 v[52:55], v[52:53], off nt
	v_add_u32_e32 v58, s14, v1
	s_ashr_i32 s13, s12, 31
	v_ashrrev_i32_e32 v59, 31, v58
	v_lshl_add_u64 v[56:57], s[12:13], 1, v[8:9]
	v_lshlrev_b64 v[64:65], 12, v[58:59]
	v_add_u32_e32 v60, 8, v58
	v_lshl_add_u64 v[64:65], v[56:57], 0, v[64:65]
	v_ashrrev_i32_e32 v61, 31, v60
	v_lshlrev_b64 v[60:61], 12, v[60:61]
	v_add_u32_e32 v62, 16, v58
	v_lshl_add_u64 v[60:61], v[56:57], 0, v[60:61]
	v_ashrrev_i32_e32 v63, 31, v62
	v_lshlrev_b64 v[62:63], 12, v[62:63]
	v_lshl_add_u64 v[62:63], v[56:57], 0, v[62:63]
	s_add_i32 s1, s1, s94
	s_add_i32 s2, s2, s3
	s_cmpk_gt_i32 s1, 0x17ff
	s_waitcnt vmcnt(7)
	ds_write2_b32 v17, v24, v25 offset1:1
	ds_write2_b32 v17, v26, v27 offset0:2 offset1:3
	s_waitcnt vmcnt(6)
	ds_write2_b32 v3, v28, v29 offset1:1
	ds_write2_b32 v5, v30, v31 offset1:1
	s_waitcnt vmcnt(5)
	ds_write2_b32 v10, v32, v33 offset1:1
	ds_write2_b32 v11, v34, v35 offset1:1
	s_waitcnt vmcnt(4)
	ds_write2_b32 v12, v36, v37 offset1:1
	ds_write2_b32 v13, v38, v39 offset1:1
	s_waitcnt vmcnt(3)
	ds_write2_b32 v14, v40, v41 offset1:1
	ds_write2_b32 v15, v42, v43 offset1:1
	s_waitcnt vmcnt(2)
	ds_write2_b32 v18, v44, v45 offset1:1
	ds_write2_b32 v19, v46, v47 offset1:1
	s_waitcnt vmcnt(1)
	ds_write2_b32 v20, v48, v49 offset1:1
	ds_write2_b32 v21, v50, v51 offset1:1
	s_waitcnt vmcnt(0)
	ds_write2_b32 v22, v52, v53 offset1:1
	ds_write2_b32 v23, v54, v55 offset1:1
	s_waitcnt lgkmcnt(0)
	ds_read2_b32 v[92:93], v16 offset1:33
	ds_read2_b32 v[94:95], v16 offset0:66 offset1:99
	ds_read2_b32 v[96:97], v16 offset0:132 offset1:165
	ds_read2_b32 v[98:99], v16 offset0:198 offset1:231
	ds_read2_b32 v[100:101], v16 offset0:8 offset1:41
	ds_read2_b32 v[102:103], v16 offset0:74 offset1:107
	ds_read2_b32 v[104:105], v16 offset0:140 offset1:173
	ds_read2_b32 v[106:107], v16 offset0:206 offset1:239
	ds_read2_b32 v[108:109], v16 offset0:16 offset1:49
	ds_read2_b32 v[110:111], v16 offset0:82 offset1:115
	ds_read2_b32 v[112:113], v16 offset0:148 offset1:181
	ds_read2_b32 v[114:115], v16 offset0:214 offset1:247
	ds_read2_b32 v[116:117], v16 offset0:24 offset1:57
	ds_read2_b32 v[118:119], v16 offset0:90 offset1:123
	ds_read2_b32 v[120:121], v16 offset0:156 offset1:189
	ds_read2_b32 v[122:123], v16 offset0:222 offset1:255
	s_waitcnt lgkmcnt(0)
	s_nop 0
	v_cvt_pk_bf16_f32 v24, v92, v93
	s_nop 0
	v_cvt_pk_bf16_f32 v25, v94, v95
	s_nop 0
	v_cvt_pk_bf16_f32 v26, v96, v97
	s_nop 0
	v_cvt_pk_bf16_f32 v27, v98, v99
	global_store_dwordx4 v[64:65], v[24:27], off
	v_add_u32_e32 v30, 24, v58
	v_ashrrev_i32_e32 v31, 31, v30
	s_nop 0
	v_cvt_pk_bf16_f32 v24, v100, v101
	s_nop 0
	v_cvt_pk_bf16_f32 v25, v102, v103
	s_nop 0
	v_cvt_pk_bf16_f32 v26, v104, v105
	s_nop 0
	v_cvt_pk_bf16_f32 v27, v106, v107
	global_store_dwordx4 v[60:61], v[24:27], off
	v_lshlrev_b64 v[30:31], 12, v[30:31]
	v_lshl_add_u64 v[30:31], v[56:57], 0, v[30:31]
	s_nop 0
	v_cvt_pk_bf16_f32 v24, v108, v109
	s_nop 0
	v_cvt_pk_bf16_f32 v25, v110, v111
	s_nop 0
	v_cvt_pk_bf16_f32 v26, v112, v113
	s_nop 0
	v_cvt_pk_bf16_f32 v27, v114, v115
	global_store_dwordx4 v[62:63], v[24:27], off
	s_nop 0
	s_nop 0
	v_cvt_pk_bf16_f32 v24, v116, v117
	s_nop 0
	v_cvt_pk_bf16_f32 v25, v118, v119
	s_nop 0
	v_cvt_pk_bf16_f32 v26, v120, v121
	s_nop 0
	v_cvt_pk_bf16_f32 v27, v122, v123
	global_store_dwordx4 v[30:31], v[24:27], off
	s_waitcnt lgkmcnt(0)
	s_cbranch_scc0 .LBB0_12

; #define LAS __attribute__((address_space(3)))
; __device__ __forceinline__ unsigned cvt_pk_bf16(float lo, float hi) { unsigned r; asm volatile("v_cvt_pk_bf16_f32 %0, %1, %2" : "=v"(r) : "v"(lo), "v"(hi)); return r; }
; __device__ __forceinline__ void p0_transpose_item(const float* W, int N, bf16_t* WT, int ldt, int coff, LAS float* scr, int item, int lane) {
;     const int nblk = N / 32, kb = item / nblk, nb = item % nblk, k0 = 64 * kb, n0 = 32 * nb;
;     { f32x4 v[8];
; #pragma unroll
;       for (int i = 0; i < 8; ++i) v[i] = __builtin_nontemporal_load((const f32x4*)(W + (size_t)(k0 + 8 * i + (lane >> 3)) * N + n0 + 4 * (lane & 7)));
; #pragma unroll
;       for (int i = 0; i < 8; ++i) { LAS float* d = scr + (8 * i + (lane >> 3)) * 33 + 4 * (lane & 7); d[0] = v[i].x; d[1] = v[i].y; d[2] = v[i].z; d[3] = v[i].w; } }
;     asm volatile("s_waitcnt lgkmcnt(0)" ::: "memory");
;     const int c = lane & 7;
; #pragma unroll
;     for (int j = 0; j < 4; ++j) { const int n = (lane >> 3) + 8 * j; const LAS float* s = scr + (8 * c) * 33 + n;
;         u32x4 o; o.x = cvt_pk_bf16(s[0 * 33], s[1 * 33]); o.y = cvt_pk_bf16(s[2 * 33], s[3 * 33]); o.z = cvt_pk_bf16(s[4 * 33], s[5 * 33]); o.w = cvt_pk_bf16(s[6 * 33], s[7 * 33]);
;         *(u32x4*)(WT + (size_t)(n0 + n) * ldt + coff + k0 + 8 * c) = o; }
;     asm volatile("s_waitcnt lgkmcnt(0)" ::: "memory");
; }
.LBB0_15:
	s_ashr_i32 s0, s11, 31
	s_lshr_b32 s0, s0, 26
	s_add_i32 s0, s11, s0
	s_and_b32 s2, s0, 0xffffffc0
	s_lshl_b32 s0, s0, 5
	s_and_b32 s0, s0, 0xfffff800
	v_or_b32_e32 v24, s2, v1
	s_sub_i32 s0, s12, s0
	v_or_b32_e32 v26, 8, v24
	v_or_b32_e32 v28, 16, v24
	v_or_b32_e32 v30, 24, v24
	v_or_b32_e32 v32, 32, v24
	v_or_b32_e32 v34, 40, v24
	v_or_b32_e32 v36, 48, v24
	v_or_b32_e32 v38, 56, v24
	v_ashrrev_i32_e32 v25, 31, v24
	s_ashr_i32 s1, s0, 31
	v_ashrrev_i32_e32 v27, 31, v26
	v_ashrrev_i32_e32 v29, 31, v28
	v_ashrrev_i32_e32 v31, 31, v30
	v_ashrrev_i32_e32 v33, 31, v32
	v_ashrrev_i32_e32 v35, 31, v34
	v_ashrrev_i32_e32 v37, 31, v36
	v_ashrrev_i32_e32 v39, 31, v38
	v_lshlrev_b64 v[24:25], 13, v[24:25]
	v_lshl_add_u64 v[40:41], s[0:1], 2, v[6:7]
	v_lshlrev_b64 v[26:27], 13, v[26:27]
	v_lshlrev_b64 v[28:29], 13, v[28:29]
	v_lshlrev_b64 v[30:31], 13, v[30:31]
	v_lshlrev_b64 v[32:33], 13, v[32:33]
	v_lshlrev_b64 v[34:35], 13, v[34:35]
	v_lshlrev_b64 v[36:37], 13, v[36:37]
	v_lshlrev_b64 v[38:39], 13, v[38:39]
	v_lshl_add_u64 v[24:25], v[40:41], 0, v[24:25]
	v_lshl_add_u64 v[42:43], v[40:41], 0, v[26:27]
	v_lshl_add_u64 v[44:45], v[40:41], 0, v[28:29]
	v_lshl_add_u64 v[46:47], v[40:41], 0, v[30:31]
	v_lshl_add_u64 v[48:49], v[40:41], 0, v[32:33]
	v_lshl_add_u64 v[50:51], v[40:41], 0, v[34:35]
	v_lshl_add_u64 v[52:53], v[40:41], 0, v[36:37]
	v_lshl_add_u64 v[54:55], v[40:41], 0, v[38:39]
	global_load_dwordx4 v[24:27], v[24:25], off nt
	s_nop 0
	global_load_dwordx4 v[28:31], v[42:43], off nt
	global_load_dwordx4 v[32:35], v[44:45], off nt
	global_load_dwordx4 v[36:39], v[46:47], off nt
	s_nop 0
	global_load_dwordx4 v[40:43], v[48:49], off nt
	global_load_dwordx4 v[44:47], v[50:51], off nt
	s_nop 0
	global_load_dwordx4 v[48:51], v[52:53], off nt
	s_nop 0
	global_load_dwordx4 v[52:55], v[54:55], off nt
	v_add_u32_e32 v58, s0, v1
	s_ashr_i32 s3, s2, 31
	v_ashrrev_i32_e32 v59, 31, v58
	v_lshl_add_u64 v[56:57], s[2:3], 1, v[8:9]
	v_lshlrev_b64 v[64:65], 12, v[58:59]
	v_add_u32_e32 v60, 8, v58
	v_lshl_add_u64 v[64:65], v[56:57], 0, v[64:65]
	v_ashrrev_i32_e32 v61, 31, v60
	v_lshlrev_b64 v[60:61], 12, v[60:61]
	v_add_u32_e32 v62, 16, v58
	v_lshl_add_u64 v[60:61], v[56:57], 0, v[60:61]
	v_ashrrev_i32_e32 v63, 31, v62
	v_lshlrev_b64 v[62:63], 12, v[62:63]
	v_lshl_add_u64 v[62:63], v[56:57], 0, v[62:63]
	s_add_i32 s11, s11, s94
	s_add_i32 s12, s12, s13
	s_cmpk_gt_i32 s11, 0x7ff
	s_waitcnt vmcnt(7)
	ds_write2_b32 v17, v24, v25 offset1:1
	ds_write2_b32 v17, v26, v27 offset0:2 offset1:3
	s_waitcnt vmcnt(6)
	ds_write2_b32 v3, v28, v29 offset1:1
	ds_write2_b32 v5, v30, v31 offset1:1
	s_waitcnt vmcnt(5)
	ds_write2_b32 v10, v32, v33 offset1:1
	ds_write2_b32 v11, v34, v35 offset1:1
	s_waitcnt vmcnt(4)
	ds_write2_b32 v12, v36, v37 offset1:1
	ds_write2_b32 v13, v38, v39 offset1:1
	s_waitcnt vmcnt(3)
	ds_write2_b32 v14, v40, v41 offset1:1
	ds_write2_b32 v15, v42, v43 offset1:1
	s_waitcnt vmcnt(2)
	ds_write2_b32 v18, v44, v45 offset1:1
	ds_write2_b32 v19, v46, v47 offset1:1
	s_waitcnt vmcnt(1)
	ds_write2_b32 v20, v48, v49 offset1:1
	ds_write2_b32 v21, v50, v51 offset1:1
	s_waitcnt vmcnt(0)
	ds_write2_b32 v22, v52, v53 offset1:1
	ds_write2_b32 v23, v54, v55 offset1:1
	s_waitcnt lgkmcnt(0)
	ds_read2_b32 v[92:93], v16 offset1:33
	ds_read2_b32 v[94:95], v16 offset0:66 offset1:99
	ds_read2_b32 v[96:97], v16 offset0:132 offset1:165
	ds_read2_b32 v[98:99], v16 offset0:198 offset1:231
	ds_read2_b32 v[100:101], v16 offset0:8 offset1:41
	ds_read2_b32 v[102:103], v16 offset0:74 offset1:107
	ds_read2_b32 v[104:105], v16 offset0:140 offset1:173
	ds_read2_b32 v[106:107], v16 offset0:206 offset1:239
	ds_read2_b32 v[108:109], v16 offset0:16 offset1:49
	ds_read2_b32 v[110:111], v16 offset0:82 offset1:115
	ds_read2_b32 v[112:113], v16 offset0:148 offset1:181
	ds_read2_b32 v[114:115], v16 offset0:214 offset1:247
	ds_read2_b32 v[116:117], v16 offset0:24 offset1:57
	ds_read2_b32 v[118:119], v16 offset0:90 offset1:123
	ds_read2_b32 v[120:121], v16 offset0:156 offset1:189
	ds_read2_b32 v[122:123], v16 offset0:222 offset1:255
	s_waitcnt lgkmcnt(0)
	s_nop 0
	v_cvt_pk_bf16_f32 v24, v92, v93
	s_nop 0
	v_cvt_pk_bf16_f32 v25, v94, v95
	s_nop 0
	v_cvt_pk_bf16_f32 v26, v96, v97
	s_nop 0
	v_cvt_pk_bf16_f32 v27, v98, v99
	global_store_dwordx4 v[64:65], v[24:27], off
	v_add_u32_e32 v30, 24, v58
	v_ashrrev_i32_e32 v31, 31, v30
	s_nop 0
	v_cvt_pk_bf16_f32 v24, v100, v101
	s_nop 0
	v_cvt_pk_bf16_f32 v25, v102, v103
	s_nop 0
	v_cvt_pk_bf16_f32 v26, v104, v105
	s_nop 0
	v_cvt_pk_bf16_f32 v27, v106, v107
	global_store_dwordx4 v[60:61], v[24:27], off
	v_lshlrev_b64 v[30:31], 12, v[30:31]
	v_lshl_add_u64 v[30:31], v[56:57], 0, v[30:31]
	s_nop 0
	v_cvt_pk_bf16_f32 v24, v108, v109
	s_nop 0
	v_cvt_pk_bf16_f32 v25, v110, v111
	s_nop 0
	v_cvt_pk_bf16_f32 v26, v112, v113
	s_nop 0
	v_cvt_pk_bf16_f32 v27, v114, v115
	global_store_dwordx4 v[62:63], v[24:27], off
	s_nop 0
	s_nop 0
	v_cvt_pk_bf16_f32 v24, v116, v117
	s_nop 0
	v_cvt_pk_bf16_f32 v25, v118, v119
	s_nop 0
	v_cvt_pk_bf16_f32 v26, v120, v121
	s_nop 0
	v_cvt_pk_bf16_f32 v27, v122, v123
	global_store_dwordx4 v[30:31], v[24:27], off
	s_waitcnt lgkmcnt(0)
	s_cbranch_scc0 .LBB0_15

; #define LAS __attribute__((address_space(3)))
; __device__ __forceinline__ unsigned cvt_pk_bf16(float lo, float hi) { unsigned r; asm volatile("v_cvt_pk_bf16_f32 %0, %1, %2" : "=v"(r) : "v"(lo), "v"(hi)); return r; }
; #define TR(Wp, K_, N_, WTp, ldt_, coff_) { const int ni = ((K_) / 64) * ((N_) / 32); int first = ((gw - base) % NGW + NGW) % NGW; \
;             for (int it = first; it < ni; it += NGW) p0_transpose_item((Wp), (N_), (bf16_t*)(WTp), (ldt_), (coff_), scr, it, F.lane); base = (base + ni) % NGW; }
; __device__ __forceinline__ void p0_transpose_item(const float* W, int N, bf16_t* WT, int ldt, int coff, LAS float* scr, int item, int lane) {
;     const int nblk = N / 32, kb = item / nblk, nb = item % nblk, k0 = 64 * kb, n0 = 32 * nb;
;     { f32x4 v[8];
; #pragma unroll
;       for (int i = 0; i < 8; ++i) v[i] = __builtin_nontemporal_load((const f32x4*)(W + (size_t)(k0 + 8 * i + (lane >> 3)) * N + n0 + 4 * (lane & 7)));
; #pragma unroll
;       for (int i = 0; i < 8; ++i) { LAS float* d = scr + (8 * i + (lane >> 3)) * 33 + 4 * (lane & 7); d[0] = v[i].x; d[1] = v[i].y; d[2] = v[i].z; d[3] = v[i].w; } }
;     asm volatile("s_waitcnt lgkmcnt(0)" ::: "memory");
;     const int c = lane & 7;
; #pragma unroll
;     for (int j = 0; j < 4; ++j) { const int n = (lane >> 3) + 8 * j; const LAS float* s = scr + (8 * c) * 33 + n;
;         u32x4 o; o.x = cvt_pk_bf16(s[0 * 33], s[1 * 33]); o.y = cvt_pk_bf16(s[2 * 33], s[3 * 33]); o.z = cvt_pk_bf16(s[4 * 33], s[5 * 33]); o.w = cvt_pk_bf16(s[6 * 33], s[7 * 33]);
;         *(u32x4*)(WT + (size_t)(n0 + n) * ldt + coff + k0 + 8 * c) = o; }
;     asm volatile("s_waitcnt lgkmcnt(0)" ::: "memory");
; }
; __device__ __forceinline__ void phase0(const Frame& F, const Args& a) {
;     ...
;         TR(a.w_o_attn, 512, D, ws + WS_WO, YP, 0)
.LBB0_18:
	s_ashr_i32 s0, s10, 31
	s_lshr_b32 s0, s0, 26
	s_add_i32 s0, s10, s0
	s_ashr_i32 s13, s0, 6
	s_andn2_b32 s0, s0, 63
	s_lshl_b32 s1, s13, 11
	v_or_b32_e32 v26, s0, v1
	s_sub_i32 s14, s11, s1
	v_or_b32_e32 v28, 8, v26
	v_or_b32_e32 v30, 16, v26
	v_or_b32_e32 v32, 24, v26
	v_or_b32_e32 v34, 32, v26
	v_or_b32_e32 v36, 40, v26
	v_or_b32_e32 v38, 48, v26
	v_or_b32_e32 v40, 56, v26
	v_ashrrev_i32_e32 v27, 31, v26
	s_ashr_i32 s15, s14, 31
	v_ashrrev_i32_e32 v29, 31, v28
	v_ashrrev_i32_e32 v31, 31, v30
	v_ashrrev_i32_e32 v33, 31, v32
	v_ashrrev_i32_e32 v35, 31, v34
	v_ashrrev_i32_e32 v37, 31, v36
	v_ashrrev_i32_e32 v39, 31, v38
	v_ashrrev_i32_e32 v41, 31, v40
	v_lshlrev_b64 v[26:27], 13, v[26:27]
	v_lshl_add_u64 v[42:43], s[14:15], 2, v[6:7]
	v_lshlrev_b64 v[28:29], 13, v[28:29]
	v_lshlrev_b64 v[30:31], 13, v[30:31]
	v_lshlrev_b64 v[32:33], 13, v[32:33]
	v_lshlrev_b64 v[34:35], 13, v[34:35]
	v_lshlrev_b64 v[36:37], 13, v[36:37]
	v_lshlrev_b64 v[38:39], 13, v[38:39]
	v_lshlrev_b64 v[40:41], 13, v[40:41]
	v_lshl_add_u64 v[26:27], v[42:43], 0, v[26:27]
	v_lshl_add_u64 v[44:45], v[42:43], 0, v[28:29]
	v_lshl_add_u64 v[46:47], v[42:43], 0, v[30:31]
	v_lshl_add_u64 v[48:49], v[42:43], 0, v[32:33]
	v_lshl_add_u64 v[50:51], v[42:43], 0, v[34:35]
	v_lshl_add_u64 v[52:53], v[42:43], 0, v[36:37]
	v_lshl_add_u64 v[54:55], v[42:43], 0, v[38:39]
	v_lshl_add_u64 v[56:57], v[42:43], 0, v[40:41]
	global_load_dwordx4 v[26:29], v[26:27], off nt
	s_nop 0
	global_load_dwordx4 v[30:33], v[44:45], off nt
	global_load_dwordx4 v[34:37], v[46:47], off nt
	global_load_dwordx4 v[38:41], v[48:49], off nt
	s_nop 0
	global_load_dwordx4 v[42:45], v[50:51], off nt
	global_load_dwordx4 v[46:49], v[52:53], off nt
	s_nop 0
	global_load_dwordx4 v[50:53], v[54:55], off nt
	s_nop 0
	global_load_dwordx4 v[54:57], v[56:57], off nt
	s_mul_i32 s13, s13, 0xff400000
	s_ashr_i32 s1, s0, 31
	v_add_u32_e32 v60, s13, v3
	v_lshl_add_u64 v[58:59], s[0:1], 1, v[8:9]
	v_ashrrev_i32_e32 v61, 31, v60
	v_lshl_add_u64 v[66:67], v[58:59], 0, v[60:61]
	v_add_u32_e32 v62, 0xc000, v60
	v_ashrrev_i32_e32 v63, 31, v62
	v_lshl_add_u64 v[62:63], v[58:59], 0, v[62:63]
	v_add_u32_e32 v64, 0x18000, v60
	v_ashrrev_i32_e32 v65, 31, v64
	v_lshl_add_u64 v[64:65], v[58:59], 0, v[64:65]
	s_add_i32 s10, s10, s94
	s_add_i32 s11, s11, s12
	s_cmpk_gt_i32 s10, 0x1ff
	v_add_u32_e32 v3, s2, v3
	s_waitcnt vmcnt(7)
	ds_write2_b32 v17, v26, v27 offset1:1
	ds_write2_b32 v17, v28, v29 offset0:2 offset1:3
	s_waitcnt vmcnt(6)
	ds_write2_b32 v5, v30, v31 offset1:1
	ds_write2_b32 v10, v32, v33 offset1:1
	s_waitcnt vmcnt(5)
	ds_write2_b32 v11, v34, v35 offset1:1
	ds_write2_b32 v12, v36, v37 offset1:1
	s_waitcnt vmcnt(4)
	ds_write2_b32 v13, v38, v39 offset1:1
	ds_write2_b32 v14, v40, v41 offset1:1
	s_waitcnt vmcnt(3)
	ds_write2_b32 v15, v42, v43 offset1:1
	ds_write2_b32 v18, v44, v45 offset1:1
	s_waitcnt vmcnt(2)
	ds_write2_b32 v19, v46, v47 offset1:1
	ds_write2_b32 v20, v48, v49 offset1:1
	s_waitcnt vmcnt(1)
	ds_write2_b32 v21, v50, v51 offset1:1
	ds_write2_b32 v22, v52, v53 offset1:1
	s_waitcnt vmcnt(0)
	ds_write2_b32 v23, v54, v55 offset1:1
	ds_write2_b32 v24, v56, v57 offset1:1
	s_waitcnt lgkmcnt(0)
	ds_read2_b32 v[92:93], v16 offset1:33
	ds_read2_b32 v[94:95], v16 offset0:66 offset1:99
	ds_read2_b32 v[96:97], v16 offset0:132 offset1:165
	ds_read2_b32 v[98:99], v16 offset0:198 offset1:231
	ds_read2_b32 v[100:101], v16 offset0:8 offset1:41
	ds_read2_b32 v[102:103], v16 offset0:74 offset1:107
	ds_read2_b32 v[104:105], v16 offset0:140 offset1:173
	ds_read2_b32 v[106:107], v16 offset0:206 offset1:239
	ds_read2_b32 v[108:109], v16 offset0:16 offset1:49
	ds_read2_b32 v[110:111], v16 offset0:82 offset1:115
	ds_read2_b32 v[112:113], v16 offset0:148 offset1:181
	ds_read2_b32 v[114:115], v16 offset0:214 offset1:247
	ds_read2_b32 v[116:117], v16 offset0:24 offset1:57
	ds_read2_b32 v[118:119], v16 offset0:90 offset1:123
	ds_read2_b32 v[120:121], v16 offset0:156 offset1:189
	ds_read2_b32 v[122:123], v16 offset0:222 offset1:255
	s_waitcnt lgkmcnt(0)
	s_nop 0
	v_cvt_pk_bf16_f32 v26, v92, v93
	s_nop 0
	v_cvt_pk_bf16_f32 v27, v94, v95
	s_nop 0
	v_cvt_pk_bf16_f32 v28, v96, v97
	s_nop 0
	v_cvt_pk_bf16_f32 v29, v98, v99
	global_store_dwordx4 v[66:67], v[26:29], off
	v_add_u32_e32 v32, 0x24000, v60
	v_ashrrev_i32_e32 v33, 31, v32
	s_nop 0
	v_cvt_pk_bf16_f32 v26, v100, v101
	s_nop 0
	v_cvt_pk_bf16_f32 v27, v102, v103
	s_nop 0
	v_cvt_pk_bf16_f32 v28, v104, v105
	s_nop 0
	v_cvt_pk_bf16_f32 v29, v106, v107
	global_store_dwordx4 v[62:63], v[26:29], off
	v_lshl_add_u64 v[32:33], v[58:59], 0, v[32:33]
	s_nop 0
	v_cvt_pk_bf16_f32 v26, v108, v109
	s_nop 0
	v_cvt_pk_bf16_f32 v27, v110, v111
	s_nop 0
	v_cvt_pk_bf16_f32 v28, v112, v113
	s_nop 0
	v_cvt_pk_bf16_f32 v29, v114, v115
	global_store_dwordx4 v[64:65], v[26:29], off
	s_nop 0
	s_nop 0
	v_cvt_pk_bf16_f32 v26, v116, v117
	s_nop 0
	v_cvt_pk_bf16_f32 v27, v118, v119
	s_nop 0
	v_cvt_pk_bf16_f32 v28, v120, v121
	s_nop 0
	v_cvt_pk_bf16_f32 v29, v122, v123
	global_store_dwordx4 v[32:33], v[26:29], off
	s_waitcnt lgkmcnt(0)
	s_cbranch_scc0 .LBB0_18

; #define LAS __attribute__((address_space(3)))
; __device__ __forceinline__ unsigned cvt_pk_bf16(float lo, float hi) { unsigned r; asm volatile("v_cvt_pk_bf16_f32 %0, %1, %2" : "=v"(r) : "v"(lo), "v"(hi)); return r; }
; #define TR(Wp, K_, N_, WTp, ldt_, coff_) { const int ni = ((K_) / 64) * ((N_) / 32); int first = ((gw - base) % NGW + NGW) % NGW; \
;             for (int it = first; it < ni; it += NGW) p0_transpose_item((Wp), (N_), (bf16_t*)(WTp), (ldt_), (coff_), scr, it, F.lane); base = (base + ni) % NGW; }
; __device__ __forceinline__ void p0_transpose_item(const float* W, int N, bf16_t* WT, int ldt, int coff, LAS float* scr, int item, int lane) {
;     const int nblk = N / 32, kb = item / nblk, nb = item % nblk, k0 = 64 * kb, n0 = 32 * nb;
;     { f32x4 v[8];
; #pragma unroll
;       for (int i = 0; i < 8; ++i) v[i] = __builtin_nontemporal_load((const f32x4*)(W + (size_t)(k0 + 8 * i + (lane >> 3)) * N + n0 + 4 * (lane & 7)));
; #pragma unroll
;       for (int i = 0; i < 8; ++i) { LAS float* d = scr + (8 * i + (lane >> 3)) * 33 + 4 * (lane & 7); d[0] = v[i].x; d[1] = v[i].y; d[2] = v[i].z; d[3] = v[i].w; } }
;     asm volatile("s_waitcnt lgkmcnt(0)" ::: "memory");
;     const int c = lane & 7;
; #pragma unroll
;     for (int j = 0; j < 4; ++j) { const int n = (lane >> 3) + 8 * j; const LAS float* s = scr + (8 * c) * 33 + n;
;         u32x4 o; o.x = cvt_pk_bf16(s[0 * 33], s[1 * 33]); o.y = cvt_pk_bf16(s[2 * 33], s[3 * 33]); o.z = cvt_pk_bf16(s[4 * 33], s[5 * 33]); o.w = cvt_pk_bf16(s[6 * 33], s[7 * 33]);
;         *(u32x4*)(WT + (size_t)(n0 + n) * ldt + coff + k0 + 8 * c) = o; }
;     asm volatile("s_waitcnt lgkmcnt(0)" ::: "memory");
; }
; __device__ __forceinline__ void phase0(const Frame& F, const Args& a) {
;     ...
;         TR(a.w_o_lru, 1536, D, ws + WS_WO, YP, 512)
.LBB0_21:
	s_ashr_i32 s0, s10, 31
	s_lshr_b32 s0, s0, 26
	s_add_i32 s0, s10, s0
	s_ashr_i32 s13, s0, 6
	s_andn2_b32 s0, s0, 63
	s_lshl_b32 s1, s13, 11
	v_or_b32_e32 v26, s0, v1
	s_sub_i32 s14, s11, s1
	v_or_b32_e32 v28, 8, v26
	v_or_b32_e32 v30, 16, v26
	v_or_b32_e32 v32, 24, v26
	v_or_b32_e32 v34, 32, v26
	v_or_b32_e32 v36, 40, v26
	v_or_b32_e32 v38, 48, v26
	v_or_b32_e32 v40, 56, v26
	v_ashrrev_i32_e32 v27, 31, v26
	s_ashr_i32 s15, s14, 31
	v_ashrrev_i32_e32 v29, 31, v28
	v_ashrrev_i32_e32 v31, 31, v30
	v_ashrrev_i32_e32 v33, 31, v32
	v_ashrrev_i32_e32 v35, 31, v34
	v_ashrrev_i32_e32 v37, 31, v36
	v_ashrrev_i32_e32 v39, 31, v38
	v_ashrrev_i32_e32 v41, 31, v40
	v_lshlrev_b64 v[26:27], 13, v[26:27]
	v_lshl_add_u64 v[42:43], s[14:15], 2, v[6:7]
	v_lshlrev_b64 v[28:29], 13, v[28:29]
	v_lshlrev_b64 v[30:31], 13, v[30:31]
	v_lshlrev_b64 v[32:33], 13, v[32:33]
	v_lshlrev_b64 v[34:35], 13, v[34:35]
	v_lshlrev_b64 v[36:37], 13, v[36:37]
	v_lshlrev_b64 v[38:39], 13, v[38:39]
	v_lshlrev_b64 v[40:41], 13, v[40:41]
	v_lshl_add_u64 v[26:27], v[42:43], 0, v[26:27]
	v_lshl_add_u64 v[44:45], v[42:43], 0, v[28:29]
	v_lshl_add_u64 v[46:47], v[42:43], 0, v[30:31]
	v_lshl_add_u64 v[48:49], v[42:43], 0, v[32:33]
	v_lshl_add_u64 v[50:51], v[42:43], 0, v[34:35]
	v_lshl_add_u64 v[52:53], v[42:43], 0, v[36:37]
	v_lshl_add_u64 v[54:55], v[42:43], 0, v[38:39]
	v_lshl_add_u64 v[56:57], v[42:43], 0, v[40:41]
	global_load_dwordx4 v[26:29], v[26:27], off nt
	s_nop 0
	global_load_dwordx4 v[30:33], v[44:45], off nt
	global_load_dwordx4 v[34:37], v[46:47], off nt
	global_load_dwordx4 v[38:41], v[48:49], off nt
	s_nop 0
	global_load_dwordx4 v[42:45], v[50:51], off nt
	global_load_dwordx4 v[46:49], v[52:53], off nt
	s_nop 0
	global_load_dwordx4 v[50:53], v[54:55], off nt
	s_nop 0
	global_load_dwordx4 v[54:57], v[56:57], off nt
	s_mul_i32 s13, s13, 0xff400000
	s_ashr_i32 s1, s0, 31
	v_add_u32_e32 v60, s13, v3
	v_lshl_add_u64 v[58:59], s[0:1], 1, v[8:9]
	v_ashrrev_i32_e32 v61, 31, v60
	v_lshl_add_u64 v[66:67], v[58:59], 0, v[60:61]
	v_add_u32_e32 v62, 0xc000, v60
	v_ashrrev_i32_e32 v63, 31, v62
	v_lshl_add_u64 v[62:63], v[58:59], 0, v[62:63]
	v_add_u32_e32 v64, 0x18000, v60
	v_ashrrev_i32_e32 v65, 31, v64
	v_lshl_add_u64 v[64:65], v[58:59], 0, v[64:65]
	s_add_i32 s10, s10, s94
	s_add_i32 s11, s11, s12
	s_cmpk_gt_i32 s10, 0x5ff
	v_add_u32_e32 v3, s2, v3
	s_waitcnt vmcnt(7)
	ds_write2_b32 v17, v26, v27 offset1:1
	ds_write2_b32 v17, v28, v29 offset0:2 offset1:3
	s_waitcnt vmcnt(6)
	ds_write2_b32 v5, v30, v31 offset1:1
	ds_write2_b32 v10, v32, v33 offset1:1
	s_waitcnt vmcnt(5)
	ds_write2_b32 v11, v34, v35 offset1:1
	ds_write2_b32 v12, v36, v37 offset1:1
	s_waitcnt vmcnt(4)
	ds_write2_b32 v13, v38, v39 offset1:1
	ds_write2_b32 v14, v40, v41 offset1:1
	s_waitcnt vmcnt(3)
	ds_write2_b32 v15, v42, v43 offset1:1
	ds_write2_b32 v18, v44, v45 offset1:1
	s_waitcnt vmcnt(2)
	ds_write2_b32 v19, v46, v47 offset1:1
	ds_write2_b32 v20, v48, v49 offset1:1
	s_waitcnt vmcnt(1)
	ds_write2_b32 v21, v50, v51 offset1:1
	ds_write2_b32 v22, v52, v53 offset1:1
	s_waitcnt vmcnt(0)
	ds_write2_b32 v23, v54, v55 offset1:1
	ds_write2_b32 v24, v56, v57 offset1:1
	s_waitcnt lgkmcnt(0)
	ds_read2_b32 v[92:93], v16 offset1:33
	ds_read2_b32 v[94:95], v16 offset0:66 offset1:99
	ds_read2_b32 v[96:97], v16 offset0:132 offset1:165
	ds_read2_b32 v[98:99], v16 offset0:198 offset1:231
	ds_read2_b32 v[100:101], v16 offset0:8 offset1:41
	ds_read2_b32 v[102:103], v16 offset0:74 offset1:107
	ds_read2_b32 v[104:105], v16 offset0:140 offset1:173
	ds_read2_b32 v[106:107], v16 offset0:206 offset1:239
	ds_read2_b32 v[108:109], v16 offset0:16 offset1:49
	ds_read2_b32 v[110:111], v16 offset0:82 offset1:115
	ds_read2_b32 v[112:113], v16 offset0:148 offset1:181
	ds_read2_b32 v[114:115], v16 offset0:214 offset1:247
	ds_read2_b32 v[116:117], v16 offset0:24 offset1:57
	ds_read2_b32 v[118:119], v16 offset0:90 offset1:123
	ds_read2_b32 v[120:121], v16 offset0:156 offset1:189
	ds_read2_b32 v[122:123], v16 offset0:222 offset1:255
	s_waitcnt lgkmcnt(0)
	s_nop 0
	v_cvt_pk_bf16_f32 v26, v92, v93
	s_nop 0
	v_cvt_pk_bf16_f32 v27, v94, v95
	s_nop 0
	v_cvt_pk_bf16_f32 v28, v96, v97
	s_nop 0
	v_cvt_pk_bf16_f32 v29, v98, v99
	global_store_dwordx4 v[66:67], v[26:29], off
	v_add_u32_e32 v32, 0x24000, v60
	v_ashrrev_i32_e32 v33, 31, v32
	s_nop 0
	v_cvt_pk_bf16_f32 v26, v100, v101
	s_nop 0
	v_cvt_pk_bf16_f32 v27, v102, v103
	s_nop 0
	v_cvt_pk_bf16_f32 v28, v104, v105
	s_nop 0
	v_cvt_pk_bf16_f32 v29, v106, v107
	global_store_dwordx4 v[62:63], v[26:29], off
	v_lshl_add_u64 v[32:33], v[58:59], 0, v[32:33]
	s_nop 0
	v_cvt_pk_bf16_f32 v26, v108, v109
	s_nop 0
	v_cvt_pk_bf16_f32 v27, v110, v111
	s_nop 0
	v_cvt_pk_bf16_f32 v28, v112, v113
	s_nop 0
	v_cvt_pk_bf16_f32 v29, v114, v115
	global_store_dwordx4 v[64:65], v[26:29], off
	s_nop 0
	s_nop 0
	v_cvt_pk_bf16_f32 v26, v116, v117
	s_nop 0
	v_cvt_pk_bf16_f32 v27, v118, v119
	s_nop 0
	v_cvt_pk_bf16_f32 v28, v120, v121
	s_nop 0
	v_cvt_pk_bf16_f32 v29, v122, v123
	global_store_dwordx4 v[32:33], v[26:29], off
	s_waitcnt lgkmcnt(0)
	s_cbranch_scc0 .LBB0_21

; #define LAS __attribute__((address_space(3)))
; __device__ __forceinline__ unsigned cvt_pk_bf16(float lo, float hi) { unsigned r; asm volatile("v_cvt_pk_bf16_f32 %0, %1, %2" : "=v"(r) : "v"(lo), "v"(hi)); return r; }
; __device__ __forceinline__ void p0_transpose_item(const float* W, int N, bf16_t* WT, int ldt, int coff, LAS float* scr, int item, int lane) {
;     const int nblk = N / 32, kb = item / nblk, nb = item % nblk, k0 = 64 * kb, n0 = 32 * nb;
;     { f32x4 v[8];
; #pragma unroll
;       for (int i = 0; i < 8; ++i) v[i] = __builtin_nontemporal_load((const f32x4*)(W + (size_t)(k0 + 8 * i + (lane >> 3)) * N + n0 + 4 * (lane & 7)));
; #pragma unroll
;       for (int i = 0; i < 8; ++i) { LAS float* d = scr + (8 * i + (lane >> 3)) * 33 + 4 * (lane & 7); d[0] = v[i].x; d[1] = v[i].y; d[2] = v[i].z; d[3] = v[i].w; } }
;     asm volatile("s_waitcnt lgkmcnt(0)" ::: "memory");
;     const int c = lane & 7;
; #pragma unroll
;     for (int j = 0; j < 4; ++j) { const int n = (lane >> 3) + 8 * j; const LAS float* s = scr + (8 * c) * 33 + n;
;         u32x4 o; o.x = cvt_pk_bf16(s[0 * 33], s[1 * 33]); o.y = cvt_pk_bf16(s[2 * 33], s[3 * 33]); o.z = cvt_pk_bf16(s[4 * 33], s[5 * 33]); o.w = cvt_pk_bf16(s[6 * 33], s[7 * 33]);
;         *(u32x4*)(WT + (size_t)(n0 + n) * ldt + coff + k0 + 8 * c) = o; }
;     asm volatile("s_waitcnt lgkmcnt(0)" ::: "memory");
; }
.LBB0_24:
	s_ashr_i32 s0, s10, 31
	s_lshr_b32 s0, s0, 26
	s_add_i32 s0, s10, s0
	s_ashr_i32 s13, s0, 6
	s_andn2_b32 s0, s0, 63
	s_lshl_b32 s1, s13, 11
	v_or_b32_e32 v26, s0, v1
	s_sub_i32 s14, s11, s1
	v_or_b32_e32 v28, 8, v26
	v_or_b32_e32 v30, 16, v26
	v_or_b32_e32 v32, 24, v26
	v_or_b32_e32 v34, 32, v26
	v_or_b32_e32 v36, 40, v26
	v_or_b32_e32 v38, 48, v26
	v_or_b32_e32 v40, 56, v26
	v_ashrrev_i32_e32 v27, 31, v26
	s_ashr_i32 s15, s14, 31
	v_ashrrev_i32_e32 v29, 31, v28
	v_ashrrev_i32_e32 v31, 31, v30
	v_ashrrev_i32_e32 v33, 31, v32
	v_ashrrev_i32_e32 v35, 31, v34
	v_ashrrev_i32_e32 v37, 31, v36
	v_ashrrev_i32_e32 v39, 31, v38
	v_ashrrev_i32_e32 v41, 31, v40
	v_lshlrev_b64 v[26:27], 13, v[26:27]
	v_lshl_add_u64 v[42:43], s[14:15], 2, v[6:7]
	v_lshlrev_b64 v[28:29], 13, v[28:29]
	v_lshlrev_b64 v[30:31], 13, v[30:31]
	v_lshlrev_b64 v[32:33], 13, v[32:33]
	v_lshlrev_b64 v[34:35], 13, v[34:35]
	v_lshlrev_b64 v[36:37], 13, v[36:37]
	v_lshlrev_b64 v[38:39], 13, v[38:39]
	v_lshlrev_b64 v[40:41], 13, v[40:41]
	v_lshl_add_u64 v[26:27], v[42:43], 0, v[26:27]
	v_lshl_add_u64 v[44:45], v[42:43], 0, v[28:29]
	v_lshl_add_u64 v[46:47], v[42:43], 0, v[30:31]
	v_lshl_add_u64 v[48:49], v[42:43], 0, v[32:33]
	v_lshl_add_u64 v[50:51], v[42:43], 0, v[34:35]
	v_lshl_add_u64 v[52:53], v[42:43], 0, v[36:37]
	v_lshl_add_u64 v[54:55], v[42:43], 0, v[38:39]
	v_lshl_add_u64 v[56:57], v[42:43], 0, v[40:41]
	global_load_dwordx4 v[26:29], v[26:27], off nt
	s_nop 0
	global_load_dwordx4 v[30:33], v[44:45], off nt
	global_load_dwordx4 v[34:37], v[46:47], off nt
	global_load_dwordx4 v[38:41], v[48:49], off nt
	s_nop 0
	global_load_dwordx4 v[42:45], v[50:51], off nt
	global_load_dwordx4 v[46:49], v[52:53], off nt
	s_nop 0
	global_load_dwordx4 v[50:53], v[54:55], off nt
	s_nop 0
	global_load_dwordx4 v[54:57], v[56:57], off nt
	s_mul_i32 s13, s13, 0xff400000
	s_ashr_i32 s1, s0, 31
	v_add_u32_e32 v60, s13, v3
	v_lshl_add_u64 v[58:59], s[0:1], 1, v[8:9]
	v_ashrrev_i32_e32 v61, 31, v60
	v_lshl_add_u64 v[66:67], v[58:59], 0, v[60:61]
	v_add_u32_e32 v62, 0xc000, v60
	v_ashrrev_i32_e32 v63, 31, v62
	v_lshl_add_u64 v[62:63], v[58:59], 0, v[62:63]
	v_add_u32_e32 v64, 0x18000, v60
	v_ashrrev_i32_e32 v65, 31, v64
	v_lshl_add_u64 v[64:65], v[58:59], 0, v[64:65]
	s_add_i32 s10, s10, s94
	s_add_i32 s11, s11, s12
	s_cmpk_gt_i32 s10, 0x3ff
	v_add_u32_e32 v3, s2, v3
	s_waitcnt vmcnt(7)
	ds_write2_b32 v17, v26, v27 offset1:1
	ds_write2_b32 v17, v28, v29 offset0:2 offset1:3
	s_waitcnt vmcnt(6)
	ds_write2_b32 v5, v30, v31 offset1:1
	ds_write2_b32 v10, v32, v33 offset1:1
	s_waitcnt vmcnt(5)
	ds_write2_b32 v11, v34, v35 offset1:1
	ds_write2_b32 v12, v36, v37 offset1:1
	s_waitcnt vmcnt(4)
	ds_write2_b32 v13, v38, v39 offset1:1
	ds_write2_b32 v14, v40, v41 offset1:1
	s_waitcnt vmcnt(3)
	ds_write2_b32 v15, v42, v43 offset1:1
	ds_write2_b32 v18, v44, v45 offset1:1
	s_waitcnt vmcnt(2)
	ds_write2_b32 v19, v46, v47 offset1:1
	ds_write2_b32 v20, v48, v49 offset1:1
	s_waitcnt vmcnt(1)
	ds_write2_b32 v21, v50, v51 offset1:1
	ds_write2_b32 v22, v52, v53 offset1:1
	s_waitcnt vmcnt(0)
	ds_write2_b32 v23, v54, v55 offset1:1
	ds_write2_b32 v24, v56, v57 offset1:1
	s_waitcnt lgkmcnt(0)
	ds_read2_b32 v[92:93], v16 offset1:33
	ds_read2_b32 v[94:95], v16 offset0:66 offset1:99
	ds_read2_b32 v[96:97], v16 offset0:132 offset1:165
	ds_read2_b32 v[98:99], v16 offset0:198 offset1:231
	ds_read2_b32 v[100:101], v16 offset0:8 offset1:41
	ds_read2_b32 v[102:103], v16 offset0:74 offset1:107
	ds_read2_b32 v[104:105], v16 offset0:140 offset1:173
	ds_read2_b32 v[106:107], v16 offset0:206 offset1:239
	ds_read2_b32 v[108:109], v16 offset0:16 offset1:49
	ds_read2_b32 v[110:111], v16 offset0:82 offset1:115
	ds_read2_b32 v[112:113], v16 offset0:148 offset1:181
	ds_read2_b32 v[114:115], v16 offset0:214 offset1:247
	ds_read2_b32 v[116:117], v16 offset0:24 offset1:57
	ds_read2_b32 v[118:119], v16 offset0:90 offset1:123
	ds_read2_b32 v[120:121], v16 offset0:156 offset1:189
	ds_read2_b32 v[122:123], v16 offset0:222 offset1:255
	s_waitcnt lgkmcnt(0)
	s_nop 0
	v_cvt_pk_bf16_f32 v26, v92, v93
	s_nop 0
	v_cvt_pk_bf16_f32 v27, v94, v95
	s_nop 0
	v_cvt_pk_bf16_f32 v28, v96, v97
	s_nop 0
	v_cvt_pk_bf16_f32 v29, v98, v99
	global_store_dwordx4 v[66:67], v[26:29], off
	v_add_u32_e32 v32, 0x24000, v60
	v_ashrrev_i32_e32 v33, 31, v32
	s_nop 0
	v_cvt_pk_bf16_f32 v26, v100, v101
	s_nop 0
	v_cvt_pk_bf16_f32 v27, v102, v103
	s_nop 0
	v_cvt_pk_bf16_f32 v28, v104, v105
	s_nop 0
	v_cvt_pk_bf16_f32 v29, v106, v107
	global_store_dwordx4 v[62:63], v[26:29], off
	v_lshl_add_u64 v[32:33], v[58:59], 0, v[32:33]
	s_nop 0
	v_cvt_pk_bf16_f32 v26, v108, v109
	s_nop 0
	v_cvt_pk_bf16_f32 v27, v110, v111
	s_nop 0
	v_cvt_pk_bf16_f32 v28, v112, v113
	s_nop 0
	v_cvt_pk_bf16_f32 v29, v114, v115
	global_store_dwordx4 v[64:65], v[26:29], off
	s_nop 0
	s_nop 0
	v_cvt_pk_bf16_f32 v26, v116, v117
	s_nop 0
	v_cvt_pk_bf16_f32 v27, v118, v119
	s_nop 0
	v_cvt_pk_bf16_f32 v28, v120, v121
	s_nop 0
	v_cvt_pk_bf16_f32 v29, v122, v123
	global_store_dwordx4 v[32:33], v[26:29], off
	s_waitcnt lgkmcnt(0)
	s_cbranch_scc0 .LBB0_24

; #define LAS __attribute__((address_space(3)))
; __device__ __forceinline__ unsigned cvt_pk_bf16(float lo, float hi) { unsigned r; asm volatile("v_cvt_pk_bf16_f32 %0, %1, %2" : "=v"(r) : "v"(lo), "v"(hi)); return r; }
; __device__ __forceinline__ void p0_transpose_item(const float* W, int N, bf16_t* WT, int ldt, int coff, LAS float* scr, int item, int lane) {
;     const int nblk = N / 32, kb = item / nblk, nb = item % nblk, k0 = 64 * kb, n0 = 32 * nb;
;     { f32x4 v[8];
; #pragma unroll
;       for (int i = 0; i < 8; ++i) v[i] = __builtin_nontemporal_load((const f32x4*)(W + (size_t)(k0 + 8 * i + (lane >> 3)) * N + n0 + 4 * (lane & 7)));
; #pragma unroll
;       for (int i = 0; i < 8; ++i) { LAS float* d = scr + (8 * i + (lane >> 3)) * 33 + 4 * (lane & 7); d[0] = v[i].x; d[1] = v[i].y; d[2] = v[i].z; d[3] = v[i].w; } }
;     asm volatile("s_waitcnt lgkmcnt(0)" ::: "memory");
;     const int c = lane & 7;
; #pragma unroll
;     for (int j = 0; j < 4; ++j) { const int n = (lane >> 3) + 8 * j; const LAS float* s = scr + (8 * c) * 33 + n;
;         u32x4 o; o.x = cvt_pk_bf16(s[0 * 33], s[1 * 33]); o.y = cvt_pk_bf16(s[2 * 33], s[3 * 33]); o.z = cvt_pk_bf16(s[4 * 33], s[5 * 33]); o.w = cvt_pk_bf16(s[6 * 33], s[7 * 33]);
;         *(u32x4*)(WT + (size_t)(n0 + n) * ldt + coff + k0 + 8 * c) = o; }
;     asm volatile("s_waitcnt lgkmcnt(0)" ::: "memory");
; }
.LBB0_30:
	s_ashr_i32 s0, s11, 31
	s_lshr_b32 s0, s0, 24
	s_add_i32 s0, s11, s0
	s_ashr_i32 s0, s0, 8
	s_lshl_b32 s2, s0, 6
	s_lshl_b32 s0, s0, 13
	v_or_b32_e32 v24, s2, v1
	s_sub_i32 s0, s12, s0
	v_or_b32_e32 v26, 8, v24
	v_or_b32_e32 v28, 16, v24
	v_or_b32_e32 v30, 24, v24
	v_or_b32_e32 v32, 32, v24
	v_or_b32_e32 v34, 40, v24
	v_or_b32_e32 v36, 48, v24
	v_or_b32_e32 v38, 56, v24
	s_ashr_i32 s1, s0, 31
	v_ashrrev_i32_e32 v25, 31, v24
	v_ashrrev_i32_e32 v27, 31, v26
	v_ashrrev_i32_e32 v29, 31, v28
	v_ashrrev_i32_e32 v31, 31, v30
	v_ashrrev_i32_e32 v33, 31, v32
	v_ashrrev_i32_e32 v35, 31, v34
	v_ashrrev_i32_e32 v37, 31, v36
	v_ashrrev_i32_e32 v39, 31, v38
	v_lshl_add_u64 v[40:41], s[0:1], 2, v[6:7]
	v_lshlrev_b64 v[24:25], 15, v[24:25]
	v_lshlrev_b64 v[42:43], 15, v[26:27]
	v_lshlrev_b64 v[28:29], 15, v[28:29]
	v_lshlrev_b64 v[30:31], 15, v[30:31]
	v_lshlrev_b64 v[32:33], 15, v[32:33]
	v_lshlrev_b64 v[34:35], 15, v[34:35]
	v_lshlrev_b64 v[36:37], 15, v[36:37]
	v_lshlrev_b64 v[38:39], 15, v[38:39]
	v_lshl_add_u64 v[24:25], v[40:41], 0, v[24:25]
	v_lshl_add_u64 v[42:43], v[40:41], 0, v[42:43]
	v_lshl_add_u64 v[44:45], v[40:41], 0, v[28:29]
	v_lshl_add_u64 v[46:47], v[40:41], 0, v[30:31]
	v_lshl_add_u64 v[48:49], v[40:41], 0, v[32:33]
	v_lshl_add_u64 v[50:51], v[40:41], 0, v[34:35]
	v_lshl_add_u64 v[52:53], v[40:41], 0, v[36:37]
	v_lshl_add_u64 v[54:55], v[40:41], 0, v[38:39]
	global_load_dwordx4 v[24:27], v[24:25], off nt
	s_nop 0
	global_load_dwordx4 v[28:31], v[42:43], off nt
	global_load_dwordx4 v[32:35], v[44:45], off nt
	global_load_dwordx4 v[36:39], v[46:47], off nt
	s_nop 0
	global_load_dwordx4 v[40:43], v[48:49], off nt
	global_load_dwordx4 v[44:47], v[50:51], off nt
	s_nop 0
	global_load_dwordx4 v[48:51], v[52:53], off nt
	s_nop 0
	global_load_dwordx4 v[52:55], v[54:55], off nt
	v_add_u32_e32 v58, s0, v1
	s_ashr_i32 s3, s2, 31
	v_ashrrev_i32_e32 v59, 31, v58
	v_lshl_add_u64 v[56:57], s[2:3], 1, v[8:9]
	v_lshlrev_b64 v[64:65], 12, v[58:59]
	v_add_u32_e32 v60, 8, v58
	v_lshl_add_u64 v[64:65], v[56:57], 0, v[64:65]
	v_ashrrev_i32_e32 v61, 31, v60
	v_lshlrev_b64 v[60:61], 12, v[60:61]
	v_add_u32_e32 v62, 16, v58
	v_lshl_add_u64 v[60:61], v[56:57], 0, v[60:61]
	v_ashrrev_i32_e32 v63, 31, v62
	v_lshlrev_b64 v[62:63], 12, v[62:63]
	v_lshl_add_u64 v[62:63], v[56:57], 0, v[62:63]
	s_add_i32 s11, s11, s94
	s_add_i32 s12, s12, s13
	s_cmpk_gt_i32 s11, 0x1fff
	s_waitcnt vmcnt(7)
	ds_write2_b32 v17, v24, v25 offset1:1
	ds_write2_b32 v17, v26, v27 offset0:2 offset1:3
	s_waitcnt vmcnt(6)
	ds_write2_b32 v3, v28, v29 offset1:1
	ds_write2_b32 v5, v30, v31 offset1:1
	s_waitcnt vmcnt(5)
	ds_write2_b32 v10, v32, v33 offset1:1
	ds_write2_b32 v11, v34, v35 offset1:1
	s_waitcnt vmcnt(4)
	ds_write2_b32 v12, v36, v37 offset1:1
	ds_write2_b32 v13, v38, v39 offset1:1
	s_waitcnt vmcnt(3)
	ds_write2_b32 v14, v40, v41 offset1:1
	ds_write2_b32 v15, v42, v43 offset1:1
	s_waitcnt vmcnt(2)
	ds_write2_b32 v18, v44, v45 offset1:1
	ds_write2_b32 v19, v46, v47 offset1:1
	s_waitcnt vmcnt(1)
	ds_write2_b32 v20, v48, v49 offset1:1
	ds_write2_b32 v21, v50, v51 offset1:1
	s_waitcnt vmcnt(0)
	ds_write2_b32 v22, v52, v53 offset1:1
	ds_write2_b32 v23, v54, v55 offset1:1
	s_waitcnt lgkmcnt(0)
	ds_read2_b32 v[92:93], v16 offset1:33
	ds_read2_b32 v[94:95], v16 offset0:66 offset1:99
	ds_read2_b32 v[96:97], v16 offset0:132 offset1:165
	ds_read2_b32 v[98:99], v16 offset0:198 offset1:231
	ds_read2_b32 v[100:101], v16 offset0:8 offset1:41
	ds_read2_b32 v[102:103], v16 offset0:74 offset1:107
	ds_read2_b32 v[104:105], v16 offset0:140 offset1:173
	ds_read2_b32 v[106:107], v16 offset0:206 offset1:239
	ds_read2_b32 v[108:109], v16 offset0:16 offset1:49
	ds_read2_b32 v[110:111], v16 offset0:82 offset1:115
	ds_read2_b32 v[112:113], v16 offset0:148 offset1:181
	ds_read2_b32 v[114:115], v16 offset0:214 offset1:247
	ds_read2_b32 v[116:117], v16 offset0:24 offset1:57
	ds_read2_b32 v[118:119], v16 offset0:90 offset1:123
	ds_read2_b32 v[120:121], v16 offset0:156 offset1:189
	ds_read2_b32 v[122:123], v16 offset0:222 offset1:255
	s_waitcnt lgkmcnt(0)
	s_nop 0
	v_cvt_pk_bf16_f32 v24, v92, v93
	s_nop 0
	v_cvt_pk_bf16_f32 v25, v94, v95
	s_nop 0
	v_cvt_pk_bf16_f32 v26, v96, v97
	s_nop 0
	v_cvt_pk_bf16_f32 v27, v98, v99
	global_store_dwordx4 v[64:65], v[24:27], off
	v_add_u32_e32 v30, 24, v58
	v_ashrrev_i32_e32 v31, 31, v30
	s_nop 0
	v_cvt_pk_bf16_f32 v24, v100, v101
	s_nop 0
	v_cvt_pk_bf16_f32 v25, v102, v103
	s_nop 0
	v_cvt_pk_bf16_f32 v26, v104, v105
	s_nop 0
	v_cvt_pk_bf16_f32 v27, v106, v107
	global_store_dwordx4 v[60:61], v[24:27], off
	v_lshlrev_b64 v[30:31], 12, v[30:31]
	v_lshl_add_u64 v[30:31], v[56:57], 0, v[30:31]
	s_nop 0
	v_cvt_pk_bf16_f32 v24, v108, v109
	s_nop 0
	v_cvt_pk_bf16_f32 v25, v110, v111
	s_nop 0
	v_cvt_pk_bf16_f32 v26, v112, v113
	s_nop 0
	v_cvt_pk_bf16_f32 v27, v114, v115
	global_store_dwordx4 v[62:63], v[24:27], off
	s_nop 0
	s_nop 0
	v_cvt_pk_bf16_f32 v24, v116, v117
	s_nop 0
	v_cvt_pk_bf16_f32 v25, v118, v119
	s_nop 0
	v_cvt_pk_bf16_f32 v26, v120, v121
	s_nop 0
	v_cvt_pk_bf16_f32 v27, v122, v123
	global_store_dwordx4 v[30:31], v[24:27], off
	s_waitcnt lgkmcnt(0)
	s_cbranch_scc0 .LBB0_30

; #define LAS __attribute__((address_space(3)))
; __device__ __forceinline__ unsigned cvt_pk_bf16(float lo, float hi) { unsigned r; asm volatile("v_cvt_pk_bf16_f32 %0, %1, %2" : "=v"(r) : "v"(lo), "v"(hi)); return r; }
; __device__ __forceinline__ void p0_transpose_item(const float* W, int N, bf16_t* WT, int ldt, int coff, LAS float* scr, int item, int lane) {
;     const int nblk = N / 32, kb = item / nblk, nb = item % nblk, k0 = 64 * kb, n0 = 32 * nb;
;     { f32x4 v[8];
; #pragma unroll
;       for (int i = 0; i < 8; ++i) v[i] = __builtin_nontemporal_load((const f32x4*)(W + (size_t)(k0 + 8 * i + (lane >> 3)) * N + n0 + 4 * (lane & 7)));
; #pragma unroll
;       for (int i = 0; i < 8; ++i) { LAS float* d = scr + (8 * i + (lane >> 3)) * 33 + 4 * (lane & 7); d[0] = v[i].x; d[1] = v[i].y; d[2] = v[i].z; d[3] = v[i].w; } }
;     asm volatile("s_waitcnt lgkmcnt(0)" ::: "memory");
;     const int c = lane & 7;
; #pragma unroll
;     for (int j = 0; j < 4; ++j) { const int n = (lane >> 3) + 8 * j; const LAS float* s = scr + (8 * c) * 33 + n;
;         u32x4 o; o.x = cvt_pk_bf16(s[0 * 33], s[1 * 33]); o.y = cvt_pk_bf16(s[2 * 33], s[3 * 33]); o.z = cvt_pk_bf16(s[4 * 33], s[5 * 33]); o.w = cvt_pk_bf16(s[6 * 33], s[7 * 33]);
;         *(u32x4*)(WT + (size_t)(n0 + n) * ldt + coff + k0 + 8 * c) = o; }
;     asm volatile("s_waitcnt lgkmcnt(0)" ::: "memory");
; }
.LBB0_33:
	s_ashr_i32 s0, s8, 31
	s_lshr_b32 s0, s0, 26
	s_add_i32 s0, s8, s0
	s_and_b32 s2, s0, 0xffffffc0
	s_lshl_b32 s0, s0, 5
	s_and_b32 s0, s0, 0xfffff800
	v_or_b32_e32 v24, s2, v1
	s_sub_i32 s0, s9, s0
	v_or_b32_e32 v26, 8, v24
	v_or_b32_e32 v28, 16, v24
	v_or_b32_e32 v30, 24, v24
	v_or_b32_e32 v32, 32, v24
	v_or_b32_e32 v34, 40, v24
	v_or_b32_e32 v36, 48, v24
	v_or_b32_e32 v38, 56, v24
	v_ashrrev_i32_e32 v25, 31, v24
	s_ashr_i32 s1, s0, 31
	v_ashrrev_i32_e32 v27, 31, v26
	v_ashrrev_i32_e32 v29, 31, v28
	v_ashrrev_i32_e32 v31, 31, v30
	v_ashrrev_i32_e32 v33, 31, v32
	v_ashrrev_i32_e32 v35, 31, v34
	v_ashrrev_i32_e32 v37, 31, v36
	v_ashrrev_i32_e32 v39, 31, v38
	v_lshlrev_b64 v[24:25], 13, v[24:25]
	v_lshl_add_u64 v[40:41], s[0:1], 2, v[6:7]
	v_lshlrev_b64 v[26:27], 13, v[26:27]
	v_lshlrev_b64 v[28:29], 13, v[28:29]
	v_lshlrev_b64 v[30:31], 13, v[30:31]
	v_lshlrev_b64 v[32:33], 13, v[32:33]
	v_lshlrev_b64 v[34:35], 13, v[34:35]
	v_lshlrev_b64 v[36:37], 13, v[36:37]
	v_lshlrev_b64 v[38:39], 13, v[38:39]
	v_lshl_add_u64 v[24:25], v[40:41], 0, v[24:25]
	v_lshl_add_u64 v[42:43], v[40:41], 0, v[26:27]
	v_lshl_add_u64 v[44:45], v[40:41], 0, v[28:29]
	v_lshl_add_u64 v[46:47], v[40:41], 0, v[30:31]
	v_lshl_add_u64 v[48:49], v[40:41], 0, v[32:33]
	v_lshl_add_u64 v[50:51], v[40:41], 0, v[34:35]
	v_lshl_add_u64 v[52:53], v[40:41], 0, v[36:37]
	v_lshl_add_u64 v[54:55], v[40:41], 0, v[38:39]
	global_load_dwordx4 v[24:27], v[24:25], off nt
	s_nop 0
	global_load_dwordx4 v[28:31], v[42:43], off nt
	global_load_dwordx4 v[32:35], v[44:45], off nt
	global_load_dwordx4 v[36:39], v[46:47], off nt
	s_nop 0
	global_load_dwordx4 v[40:43], v[48:49], off nt
	global_load_dwordx4 v[44:47], v[50:51], off nt
	s_nop 0
	global_load_dwordx4 v[48:51], v[52:53], off nt
	s_nop 0
	global_load_dwordx4 v[52:55], v[54:55], off nt
	v_add_u32_e32 v58, s0, v1
	s_ashr_i32 s3, s2, 31
	v_ashrrev_i32_e32 v59, 31, v58
	v_lshl_add_u64 v[56:57], s[2:3], 1, v[8:9]
	v_lshlrev_b64 v[64:65], 14, v[58:59]
	v_add_u32_e32 v60, 8, v58
	v_lshl_add_u64 v[64:65], v[56:57], 0, v[64:65]
	v_ashrrev_i32_e32 v61, 31, v60
	v_lshlrev_b64 v[60:61], 14, v[60:61]
	v_add_u32_e32 v62, 16, v58
	v_lshl_add_u64 v[60:61], v[56:57], 0, v[60:61]
	v_ashrrev_i32_e32 v63, 31, v62
	v_lshlrev_b64 v[62:63], 14, v[62:63]
	v_lshl_add_u64 v[62:63], v[56:57], 0, v[62:63]
	s_add_i32 s8, s8, s94
	s_add_i32 s9, s9, s10
	s_cmpk_gt_i32 s8, 0x1fff
	s_waitcnt vmcnt(7)
	ds_write2_b32 v17, v24, v25 offset1:1
	ds_write2_b32 v17, v26, v27 offset0:2 offset1:3
	s_waitcnt vmcnt(6)
	ds_write2_b32 v3, v28, v29 offset1:1
	ds_write2_b32 v5, v30, v31 offset1:1
	s_waitcnt vmcnt(5)
	ds_write2_b32 v10, v32, v33 offset1:1
	ds_write2_b32 v11, v34, v35 offset1:1
	s_waitcnt vmcnt(4)
	ds_write2_b32 v12, v36, v37 offset1:1
	ds_write2_b32 v13, v38, v39 offset1:1
	s_waitcnt vmcnt(3)
	ds_write2_b32 v14, v40, v41 offset1:1
	ds_write2_b32 v15, v42, v43 offset1:1
	s_waitcnt vmcnt(2)
	ds_write2_b32 v18, v44, v45 offset1:1
	ds_write2_b32 v19, v46, v47 offset1:1
	s_waitcnt vmcnt(1)
	ds_write2_b32 v20, v48, v49 offset1:1
	ds_write2_b32 v21, v50, v51 offset1:1
	s_waitcnt vmcnt(0)
	ds_write2_b32 v22, v52, v53 offset1:1
	ds_write2_b32 v23, v54, v55 offset1:1
	s_waitcnt lgkmcnt(0)
	ds_read2_b32 v[92:93], v16 offset1:33
	ds_read2_b32 v[94:95], v16 offset0:66 offset1:99
	ds_read2_b32 v[96:97], v16 offset0:132 offset1:165
	ds_read2_b32 v[98:99], v16 offset0:198 offset1:231
	ds_read2_b32 v[100:101], v16 offset0:8 offset1:41
	ds_read2_b32 v[102:103], v16 offset0:74 offset1:107
	ds_read2_b32 v[104:105], v16 offset0:140 offset1:173
	ds_read2_b32 v[106:107], v16 offset0:206 offset1:239
	ds_read2_b32 v[108:109], v16 offset0:16 offset1:49
	ds_read2_b32 v[110:111], v16 offset0:82 offset1:115
	ds_read2_b32 v[112:113], v16 offset0:148 offset1:181
	ds_read2_b32 v[114:115], v16 offset0:214 offset1:247
	ds_read2_b32 v[116:117], v16 offset0:24 offset1:57
	ds_read2_b32 v[118:119], v16 offset0:90 offset1:123
	ds_read2_b32 v[120:121], v16 offset0:156 offset1:189
	ds_read2_b32 v[122:123], v16 offset0:222 offset1:255
	s_waitcnt lgkmcnt(0)
	s_nop 0
	v_cvt_pk_bf16_f32 v24, v92, v93
	s_nop 0
	v_cvt_pk_bf16_f32 v25, v94, v95
	s_nop 0
	v_cvt_pk_bf16_f32 v26, v96, v97
	s_nop 0
	v_cvt_pk_bf16_f32 v27, v98, v99
	global_store_dwordx4 v[64:65], v[24:27], off
	v_add_u32_e32 v30, 24, v58
	v_ashrrev_i32_e32 v31, 31, v30
	s_nop 0
	v_cvt_pk_bf16_f32 v24, v100, v101
	s_nop 0
	v_cvt_pk_bf16_f32 v25, v102, v103
	s_nop 0
	v_cvt_pk_bf16_f32 v26, v104, v105
	s_nop 0
	v_cvt_pk_bf16_f32 v27, v106, v107
	global_store_dwordx4 v[60:61], v[24:27], off
	v_lshlrev_b64 v[30:31], 14, v[30:31]
	v_lshl_add_u64 v[30:31], v[56:57], 0, v[30:31]
	s_nop 0
	v_cvt_pk_bf16_f32 v24, v108, v109
	s_nop 0
	v_cvt_pk_bf16_f32 v25, v110, v111
	s_nop 0
	v_cvt_pk_bf16_f32 v26, v112, v113
	s_nop 0
	v_cvt_pk_bf16_f32 v27, v114, v115
	global_store_dwordx4 v[62:63], v[24:27], off
	s_nop 0
	s_nop 0
	v_cvt_pk_bf16_f32 v24, v116, v117
	s_nop 0
	v_cvt_pk_bf16_f32 v25, v118, v119
	s_nop 0
	v_cvt_pk_bf16_f32 v26, v120, v121
	s_nop 0
	v_cvt_pk_bf16_f32 v27, v122, v123
	global_store_dwordx4 v[30:31], v[24:27], off
	s_waitcnt lgkmcnt(0)
	s_cbranch_scc0 .LBB0_33

; #define LAS __attribute__((address_space(3)))
; __device__ __forceinline__ unsigned cvt_pk_bf16(float lo, float hi) { unsigned r; asm volatile("v_cvt_pk_bf16_f32 %0, %1, %2" : "=v"(r) : "v"(lo), "v"(hi)); return r; }
; __device__ __forceinline__ void p0_transpose_item(const float* W, int N, bf16_t* WT, int ldt, int coff, LAS float* scr, int item, int lane) {
;     const int nblk = N / 32, kb = item / nblk, nb = item % nblk, k0 = 64 * kb, n0 = 32 * nb;
;     { f32x4 v[8];
; #pragma unroll
;       for (int i = 0; i < 8; ++i) v[i] = __builtin_nontemporal_load((const f32x4*)(W + (size_t)(k0 + 8 * i + (lane >> 3)) * N + n0 + 4 * (lane & 7)));
; #pragma unroll
;       for (int i = 0; i < 8; ++i) { LAS float* d = scr + (8 * i + (lane >> 3)) * 33 + 4 * (lane & 7); d[0] = v[i].x; d[1] = v[i].y; d[2] = v[i].z; d[3] = v[i].w; } }
;     asm volatile("s_waitcnt lgkmcnt(0)" ::: "memory");
;     const int c = lane & 7;
; #pragma unroll
;     for (int j = 0; j < 4; ++j) { const int n = (lane >> 3) + 8 * j; const LAS float* s = scr + (8 * c) * 33 + n;
;         u32x4 o; o.x = cvt_pk_bf16(s[0 * 33], s[1 * 33]); o.y = cvt_pk_bf16(s[2 * 33], s[3 * 33]); o.z = cvt_pk_bf16(s[4 * 33], s[5 * 33]); o.w = cvt_pk_bf16(s[6 * 33], s[7 * 33]);
;         *(u32x4*)(WT + (size_t)(n0 + n) * ldt + coff + k0 + 8 * c) = o; }
;     asm volatile("s_waitcnt lgkmcnt(0)" ::: "memory");
; }
; __device__ __forceinline__ void phase0(const Frame& F, const Args& a) {
;     ...
;         for (int it = gw; it < 48 * 8; it += NGW) { const int mat = it >> 3, sub = it & 7; const int which = mat / 24, dn = mat % 24;
;             const float* W = (which ? a.lru_wi : a.lru_wa) + (size_t)dn * 16384;
;             p0_transpose_item(W, 128, (bf16_t*)(ws + WS_WLRU) + (size_t)(dn * 2 + which) * 16384, 128, 0, scr, sub, F.lane); }
.LBB0_36:
	s_ashr_i32 s15, s14, 3
	s_mul_hi_i32 s16, s15, 0x2aaaaaab
	s_lshr_b32 s18, s16, 31
	s_ashr_i32 s16, s16, 2
	s_add_i32 s28, s16, s18
	s_mul_i32 s16, s28, 24
	s_add_i32 s17, s15, 23
	s_sub_i32 s16, s15, s16
	s_cmp_lt_u32 s17, 47
	s_cselect_b32 s15, s85, s89
	s_cselect_b32 s29, s84, s88
	s_ashr_i32 s17, s16, 31
	s_lshl_b64 s[18:19], s[16:17], 16
	s_add_u32 s18, s29, s18
	s_addc_u32 s15, s15, s19
	s_lshl_b32 s16, s16, 1
	s_add_i32 s16, s16, s28
	s_ashr_i32 s17, s16, 31
	s_lshl_b64 s[16:17], s[16:17], 15
	s_add_u32 s19, s2, s16
	s_addc_u32 s28, s3, s17
	s_and_b32 s29, s8, 64
	s_add_u32 s16, s18, s0
	v_or_b32_e32 v14, s29, v1
	s_addc_u32 s17, s15, s1
	v_lshlrev_b32_e32 v14, 9, v14
	v_lshl_add_u64 v[32:33], s[16:17], 0, v[2:3]
	v_lshl_add_u64 v[36:37], v[32:33], 0, v[14:15]
	v_add_co_u32_e32 v40, vcc, s10, v36
	global_load_dwordx4 v[32:35], v[36:37], off nt
	s_nop 0
	v_addc_co_u32_e32 v41, vcc, 0, v37, vcc
	v_add_co_u32_e32 v48, vcc, s11, v36
	s_lshl_b32 s15, s29, 1
	s_nop 0
	v_addc_co_u32_e32 v49, vcc, 0, v37, vcc
	v_add_co_u32_e32 v56, vcc, s12, v36
	s_add_u32 s16, s19, s15
	s_nop 0
	v_addc_co_u32_e32 v57, vcc, 0, v37, vcc
	v_add_co_u32_e32 v60, vcc, s13, v36
	s_addc_u32 s17, s28, 0
	s_nop 0
	v_addc_co_u32_e32 v61, vcc, 0, v37, vcc
	global_load_dwordx4 v[36:39], v[40:41], off offset:-4096 nt
	s_nop 0
	global_load_dwordx4 v[40:43], v[40:41], off nt
	s_nop 0
	global_load_dwordx4 v[44:47], v[48:49], off offset:-4096 nt
	s_nop 0
	global_load_dwordx4 v[48:51], v[48:49], off nt
	s_nop 0
	global_load_dwordx4 v[52:55], v[56:57], off offset:-4096 nt
	s_nop 0
	global_load_dwordx4 v[56:59], v[56:57], off nt
	s_nop 0
	global_load_dwordx4 v[60:63], v[60:61], off nt
	v_lshl_add_u64 v[64:65], s[16:17], 0, v[4:5]
	v_lshl_add_u64 v[66:67], v[64:65], 0, v[6:7]
	v_lshl_add_u64 v[68:69], v[64:65], 0, v[8:9]
	v_lshl_add_u64 v[70:71], v[64:65], 0, v[10:11]
	s_add_i32 s14, s14, s94
	s_add_i32 s8, s8, s9
	s_cmpk_gt_i32 s14, 0x17f
	s_waitcnt vmcnt(7)
	ds_write2_b32 v17, v32, v33 offset1:1
	ds_write2_b32 v17, v34, v35 offset0:2 offset1:3
	s_waitcnt vmcnt(6)
	ds_write2_b32 v18, v36, v37 offset1:1
	ds_write2_b32 v19, v38, v39 offset1:1
	s_waitcnt vmcnt(5)
	ds_write2_b32 v20, v40, v41 offset1:1
	ds_write2_b32 v21, v42, v43 offset1:1
	s_waitcnt vmcnt(4)
	ds_write2_b32 v22, v44, v45 offset1:1
	ds_write2_b32 v23, v46, v47 offset1:1
	s_waitcnt vmcnt(3)
	ds_write2_b32 v24, v48, v49 offset1:1
	ds_write2_b32 v25, v50, v51 offset1:1
	s_waitcnt vmcnt(2)
	ds_write2_b32 v26, v52, v53 offset1:1
	ds_write2_b32 v27, v54, v55 offset1:1
	s_waitcnt vmcnt(1)
	ds_write2_b32 v28, v56, v57 offset1:1
	ds_write2_b32 v29, v58, v59 offset1:1
	s_waitcnt vmcnt(0)
	ds_write2_b32 v30, v60, v61 offset1:1
	ds_write2_b32 v31, v62, v63 offset1:1
	s_waitcnt lgkmcnt(0)
	ds_read2_b32 v[92:93], v16 offset1:33
	ds_read2_b32 v[94:95], v16 offset0:66 offset1:99
	ds_read2_b32 v[96:97], v16 offset0:132 offset1:165
	ds_read2_b32 v[98:99], v16 offset0:198 offset1:231
	ds_read2_b32 v[100:101], v16 offset0:8 offset1:41
	ds_read2_b32 v[102:103], v16 offset0:74 offset1:107
	ds_read2_b32 v[104:105], v16 offset0:140 offset1:173
	ds_read2_b32 v[106:107], v16 offset0:206 offset1:239
	ds_read2_b32 v[108:109], v16 offset0:16 offset1:49
	ds_read2_b32 v[110:111], v16 offset0:82 offset1:115
	ds_read2_b32 v[112:113], v16 offset0:148 offset1:181
	ds_read2_b32 v[114:115], v16 offset0:214 offset1:247
	ds_read2_b32 v[116:117], v16 offset0:24 offset1:57
	ds_read2_b32 v[118:119], v16 offset0:90 offset1:123
	ds_read2_b32 v[120:121], v16 offset0:156 offset1:189
	ds_read2_b32 v[122:123], v16 offset0:222 offset1:255
	s_waitcnt lgkmcnt(0)
	s_nop 0
	v_cvt_pk_bf16_f32 v32, v92, v93
	s_nop 0
	v_cvt_pk_bf16_f32 v33, v94, v95
	s_nop 0
	v_cvt_pk_bf16_f32 v34, v96, v97
	s_nop 0
	v_cvt_pk_bf16_f32 v35, v98, v99
	global_store_dwordx4 v[66:67], v[32:35], off
	v_lshl_add_u64 v[38:39], v[64:65], 0, v[12:13]
	s_nop 0
	v_cvt_pk_bf16_f32 v32, v100, v101
	s_nop 0
	v_cvt_pk_bf16_f32 v33, v102, v103
	s_nop 0
	v_cvt_pk_bf16_f32 v34, v104, v105
	s_nop 0
	v_cvt_pk_bf16_f32 v35, v106, v107
	global_store_dwordx4 v[68:69], v[32:35], off
	s_nop 0
	s_nop 0
	v_cvt_pk_bf16_f32 v32, v108, v109
	s_nop 0
	v_cvt_pk_bf16_f32 v33, v110, v111
	s_nop 0
	v_cvt_pk_bf16_f32 v34, v112, v113
	s_nop 0
	v_cvt_pk_bf16_f32 v35, v114, v115
	global_store_dwordx4 v[70:71], v[32:35], off
	s_nop 0
	s_nop 0
	v_cvt_pk_bf16_f32 v32, v116, v117
	s_nop 0
	v_cvt_pk_bf16_f32 v33, v118, v119
	s_nop 0
	v_cvt_pk_bf16_f32 v34, v120, v121
	s_nop 0
	v_cvt_pk_bf16_f32 v35, v122, v123
	global_store_dwordx4 v[38:39], v[32:35], off
	s_waitcnt lgkmcnt(0)
	s_cbranch_scc0 .LBB0_36

; __device__ __forceinline__ float ub0(unsigned w) { return (float)(w & 0xffu); }
; __device__ __forceinline__ float ub1(unsigned w) { return (float)((w >> 8) & 0xffu); }
; __device__ __forceinline__ float ub2(unsigned w) { return (float)((w >> 16) & 0xffu); }
; __device__ __forceinline__ float ub3(unsigned w) { return (float)(w >> 24); }
;     __device__ __forceinline__ void mid(f32x4 (&acc)[2][2][4][2], const Unit& u, int wr, int wc, int fr, int fq, int t) const {
;         const int offx = (t == 8) ? 0 : 2048;
;         const unsigned char* gp0 = gates + (size_t)(u.pm * BM + wr * 64 + fr) * GP8 + u.pn * BM + wc * 32 + 8 * fq + offx;
; #pragma unroll
;         for (int ai = 0; ai < 2; ++ai) {
;             u32x2 gx[4][2], gy[4][2];
; #pragma unroll
;             for (int m = 0; m < 4; ++m)
; #pragma unroll
;                 for (int bj = 0; bj < 2; ++bj) { const unsigned char* gp = gp0 + (size_t)(ai * HALF + m * 16) * GP8 + bj * HALF; gx[m][bj] = *(const u32x2*)gp; gy[m][bj] = *(const u32x2*)(gp + 2048); }
; #pragma unroll
;             for (int m = 0; m < 4; ++m)
; #pragma unroll
;                 for (int bj = 0; bj < 2; ++bj) { const u32x2 x = gx[m][bj], y = gy[m][bj];
;                     f32x4 r0, r1;
;                     r0[0] = __fdividef(ub0(x.x), ub0(y.x)); r0[1] = __fdividef(ub1(x.x), ub1(y.x)); r0[2] = __fdividef(ub2(x.x), ub2(y.x)); r0[3] = __fdividef(ub3(x.x), ub3(y.x));
;                     r1[0] = __fdividef(ub0(x.y), ub0(y.y)); r1[1] = __fdividef(ub1(x.y), ub1(y.y)); r1[2] = __fdividef(ub2(x.y), ub2(y.y)); r1[3] = __fdividef(ub3(x.y), ub3(y.y));
;                     acc[ai][bj][m][0] *= r0; acc[ai][bj][m][1] *= r1; }
.LBB0_959:
	s_andn2_b64 vcc, exec, s[4:5]
	s_cbranch_vccnz .LBB0_961
	s_cmpk_eq_i32 s44, 0x300
	s_cselect_b32 s12, 0, 0x800
	v_lshl_add_u64 v[2:3], v[158:159], 0, s[12:13]
	global_load_dwordx2 v[198:199], v[2:3], off
	global_load_dwordx2 v[200:201], v[2:3], off offset:2048
	global_load_dwordx2 v[188:189], v[2:3], off offset:2176
	global_load_dwordx2 v[190:191], v[2:3], off offset:128
	v_add_co_u32_e32 v164, vcc, 0x44000, v2
	s_nop 1
	v_addc_co_u32_e32 v165, vcc, 0, v3, vcc
	v_add_co_u32_e32 v166, vcc, 0x88000, v2
	global_load_dwordx2 v[186:187], v[164:165], off
	global_load_dwordx2 v[184:185], v[164:165], off offset:2048
	global_load_dwordx2 v[180:181], v[164:165], off offset:2176
	global_load_dwordx2 v[182:183], v[164:165], off offset:128
	v_addc_co_u32_e32 v167, vcc, 0, v3, vcc
	v_add_co_u32_e32 v202, vcc, 0xcc000, v2
	global_load_dwordx2 v[178:179], v[166:167], off
	global_load_dwordx2 v[176:177], v[166:167], off offset:2048
	global_load_dwordx2 v[172:173], v[166:167], off offset:2176
	global_load_dwordx2 v[174:175], v[166:167], off offset:128
	v_addc_co_u32_e32 v203, vcc, 0, v3, vcc
	global_load_dwordx2 v[170:171], v[202:203], off
	global_load_dwordx2 v[168:169], v[202:203], off offset:2048
	global_load_dwordx2 v[164:165], v[202:203], off offset:2176
	global_load_dwordx2 v[166:167], v[202:203], off offset:128
	s_waitcnt vmcnt(12)
	v_cvt_f32_ubyte2_e32 v1, v198
	v_cvt_f32_ubyte3_e32 v204, v198
	v_cvt_f32_ubyte0_e32 v202, v198
	v_cvt_f32_ubyte1_e32 v198, v198
	v_cvt_f32_ubyte2_e32 v206, v200
	v_cvt_f32_ubyte3_e32 v205, v200
	v_cvt_f32_ubyte0_e32 v207, v200
	v_cvt_f32_ubyte1_e32 v200, v200
	v_rcp_f32_e32 v203, v200
	s_nop 0
	v_mul_f32_e32 v203, v198, v203
	v_rcp_f32_e32 v198, v207
	s_nop 0
	v_mul_f32_e32 v202, v202, v198
	v_rcp_f32_e32 v198, v205
	s_nop 0
	v_mul_f32_e32 v205, v204, v198
	v_cvt_f32_ubyte2_e32 v208, v199
	v_cvt_f32_ubyte3_e32 v209, v199
	v_rcp_f32_e32 v198, v206
	s_nop 0
	v_mul_f32_e32 v204, v1, v198
	v_cvt_f32_ubyte0_e32 v1, v199
	v_cvt_f32_ubyte1_e32 v198, v199
	v_cvt_f32_ubyte1_e32 v199, v201
	v_cvt_f32_ubyte2_e32 v207, v201
	v_cvt_f32_ubyte3_e32 v210, v201
	v_cvt_f32_ubyte0_e32 v201, v201
	v_rcp_f32_e32 v200, v199
	s_nop 0
	v_mul_f32_e32 v199, v198, v200
	v_pk_mul_f32 v[128:129], v[128:129], v[202:203]
	v_rcp_f32_e32 v198, v201
	s_nop 0
	v_mul_f32_e32 v198, v1, v198
	v_pk_mul_f32 v[124:125], v[124:125], v[198:199]
	v_rcp_f32_e32 v1, v210
	s_nop 0
	v_mul_f32_e32 v201, v209, v1
	v_cvt_f32_ubyte0_e32 v198, v190
	v_rcp_f32_e32 v1, v207
	s_nop 0
	v_mul_f32_e32 v200, v208, v1
	v_pk_mul_f32 v[126:127], v[126:127], v[200:201]
	v_cvt_f32_ubyte2_e32 v1, v190
	v_cvt_f32_ubyte3_e32 v200, v190
	v_cvt_f32_ubyte1_e32 v190, v190
	v_cvt_f32_ubyte1_e32 v199, v188
	v_pk_mul_f32 v[130:131], v[130:131], v[204:205]
	v_cvt_f32_ubyte2_e32 v203, v188
	v_cvt_f32_ubyte3_e32 v204, v188
	v_cvt_f32_ubyte0_e32 v188, v188
	v_rcp_f32_e32 v201, v199
	s_nop 0
	v_mul_f32_e32 v199, v190, v201
	v_rcp_f32_e32 v190, v188
	s_nop 0
	v_mul_f32_e32 v198, v198, v190
	v_cvt_f32_ubyte0_e32 v207, v189
	v_rcp_f32_e32 v188, v204
	s_nop 0
	v_mul_f32_e32 v201, v200, v188
	v_cvt_f32_ubyte2_e32 v205, v189
	v_rcp_f32_e32 v188, v203
	s_nop 0
	v_mul_f32_e32 v200, v1, v188
	v_cvt_f32_ubyte2_e32 v1, v191
	v_cvt_f32_ubyte3_e32 v190, v191
	v_cvt_f32_ubyte0_e32 v188, v191
	v_cvt_f32_ubyte1_e32 v191, v191
	v_cvt_f32_ubyte1_e32 v202, v189
	v_cvt_f32_ubyte3_e32 v206, v189
	v_pk_mul_f32 v[120:121], v[120:121], v[198:199]
	v_pk_mul_f32 v[122:123], v[122:123], v[200:201]
	v_rcp_f32_e32 v189, v202
	s_nop 0
	v_mul_f32_e32 v189, v191, v189
	s_waitcnt vmcnt(10)
	v_cvt_f32_ubyte2_e32 v199, v184
	v_rcp_f32_e32 v191, v207
	s_nop 0
	v_mul_f32_e32 v188, v188, v191
	v_pk_mul_f32 v[116:117], v[116:117], v[188:189]
	v_rcp_f32_e32 v191, v206
	s_nop 0
	v_mul_f32_e32 v191, v190, v191
	v_cvt_f32_ubyte0_e32 v188, v186
	v_rcp_f32_e32 v190, v205
	s_nop 0
	v_mul_f32_e32 v190, v1, v190
	v_pk_mul_f32 v[118:119], v[118:119], v[190:191]
	v_cvt_f32_ubyte2_e32 v1, v186
	v_cvt_f32_ubyte3_e32 v190, v186
	v_cvt_f32_ubyte1_e32 v186, v186
	v_cvt_f32_ubyte1_e32 v189, v184
	v_cvt_f32_ubyte3_e32 v200, v184
	v_cvt_f32_ubyte0_e32 v184, v184
	v_rcp_f32_e32 v191, v189
	s_nop 0
	v_mul_f32_e32 v189, v186, v191
	v_rcp_f32_e32 v186, v184
	s_nop 0
	v_mul_f32_e32 v188, v188, v186
	v_cvt_f32_ubyte0_e32 v203, v185
	v_rcp_f32_e32 v184, v200
	s_nop 0
	v_mul_f32_e32 v191, v190, v184
	v_cvt_f32_ubyte2_e32 v201, v185
	v_rcp_f32_e32 v184, v199
	s_nop 0
	v_mul_f32_e32 v190, v1, v184
	v_cvt_f32_ubyte2_e32 v1, v187
	v_cvt_f32_ubyte3_e32 v186, v187
	v_cvt_f32_ubyte0_e32 v184, v187
	v_cvt_f32_ubyte1_e32 v187, v187
	v_cvt_f32_ubyte1_e32 v198, v185
	v_cvt_f32_ubyte3_e32 v202, v185
	v_pk_mul_f32 v[112:113], v[112:113], v[188:189]
	v_pk_mul_f32 v[114:115], v[114:115], v[190:191]
	v_rcp_f32_e32 v185, v198
	s_nop 0
	v_mul_f32_e32 v185, v187, v185
	s_waitcnt vmcnt(9)
	v_cvt_f32_ubyte2_e32 v189, v180
	v_rcp_f32_e32 v187, v203
	s_nop 0
	v_mul_f32_e32 v184, v184, v187
	v_pk_mul_f32 v[108:109], v[108:109], v[184:185]
	v_rcp_f32_e32 v187, v202
	s_nop 0
	v_mul_f32_e32 v187, v186, v187
	s_waitcnt vmcnt(8)
	v_cvt_f32_ubyte0_e32 v184, v182
	v_rcp_f32_e32 v186, v201
	s_nop 0
	v_mul_f32_e32 v186, v1, v186
	v_pk_mul_f32 v[110:111], v[110:111], v[186:187]
	v_cvt_f32_ubyte2_e32 v1, v182
	v_cvt_f32_ubyte3_e32 v186, v182
	v_cvt_f32_ubyte1_e32 v182, v182
	v_cvt_f32_ubyte1_e32 v185, v180
	v_cvt_f32_ubyte3_e32 v190, v180
	v_cvt_f32_ubyte0_e32 v180, v180
	v_rcp_f32_e32 v187, v185
	s_nop 0
	v_mul_f32_e32 v185, v182, v187
	v_rcp_f32_e32 v182, v180
	s_nop 0
	v_mul_f32_e32 v184, v184, v182
	v_cvt_f32_ubyte0_e32 v199, v181
	v_rcp_f32_e32 v180, v190
	s_nop 0
	v_mul_f32_e32 v187, v186, v180
	v_cvt_f32_ubyte2_e32 v191, v181
	v_rcp_f32_e32 v180, v189
	s_nop 0
	v_mul_f32_e32 v186, v1, v180
	v_cvt_f32_ubyte2_e32 v1, v183
	v_cvt_f32_ubyte3_e32 v182, v183
	v_cvt_f32_ubyte0_e32 v180, v183
	v_cvt_f32_ubyte1_e32 v183, v183
	v_cvt_f32_ubyte1_e32 v188, v181
	v_cvt_f32_ubyte3_e32 v198, v181
	v_pk_mul_f32 v[104:105], v[104:105], v[184:185]
	v_pk_mul_f32 v[106:107], v[106:107], v[186:187]
	v_rcp_f32_e32 v181, v188
	s_nop 0
	v_mul_f32_e32 v181, v183, v181
	s_waitcnt vmcnt(6)
; __device__ __forceinline__ float ub0(unsigned w) { return (float)(w & 0xffu); }
; __device__ __forceinline__ float ub1(unsigned w) { return (float)((w >> 8) & 0xffu); }
; __device__ __forceinline__ float ub2(unsigned w) { return (float)((w >> 16) & 0xffu); }
; __device__ __forceinline__ float ub3(unsigned w) { return (float)(w >> 24); }
;     __device__ __forceinline__ void mid(f32x4 (&acc)[2][2][4][2], const Unit& u, int wr, int wc, int fr, int fq, int t) const {
;     ...
;                 for (int bj = 0; bj < 2; ++bj) { const unsigned char* gp = gp0 + (size_t)(ai * HALF + m * 16) * GP8 + bj * HALF; gx[m][bj] = *(const u32x2*)gp; gy[m][bj] = *(const u32x2*)(gp + 2048); }
; #pragma unroll
;             for (int m = 0; m < 4; ++m)
; #pragma unroll
;                 for (int bj = 0; bj < 2; ++bj) { const u32x2 x = gx[m][bj], y = gy[m][bj];
;                     f32x4 r0, r1;
;                     r0[0] = __fdividef(ub0(x.x), ub0(y.x)); r0[1] = __fdividef(ub1(x.x), ub1(y.x)); r0[2] = __fdividef(ub2(x.x), ub2(y.x)); r0[3] = __fdividef(ub3(x.x), ub3(y.x));
;                     r1[0] = __fdividef(ub0(x.y), ub0(y.y)); r1[1] = __fdividef(ub1(x.y), ub1(y.y)); r1[2] = __fdividef(ub2(x.y), ub2(y.y)); r1[3] = __fdividef(ub3(x.y), ub3(y.y));
;                     acc[ai][bj][m][0] *= r0; acc[ai][bj][m][1] *= r1; }
	v_cvt_f32_ubyte2_e32 v185, v176
	v_rcp_f32_e32 v183, v199
	s_nop 0
	v_mul_f32_e32 v180, v180, v183
	v_pk_mul_f32 v[100:101], v[100:101], v[180:181]
	v_rcp_f32_e32 v183, v198
	s_nop 0
	v_mul_f32_e32 v183, v182, v183
	v_cvt_f32_ubyte0_e32 v180, v178
	v_rcp_f32_e32 v182, v191
	s_nop 0
	v_mul_f32_e32 v182, v1, v182
	v_pk_mul_f32 v[102:103], v[102:103], v[182:183]
	v_cvt_f32_ubyte2_e32 v1, v178
	v_cvt_f32_ubyte3_e32 v182, v178
	v_cvt_f32_ubyte1_e32 v178, v178
	v_cvt_f32_ubyte1_e32 v181, v176
	v_cvt_f32_ubyte3_e32 v186, v176
	v_cvt_f32_ubyte0_e32 v176, v176
	v_rcp_f32_e32 v183, v181
	s_nop 0
	v_mul_f32_e32 v181, v178, v183
	v_rcp_f32_e32 v178, v176
	s_nop 0
	v_mul_f32_e32 v180, v180, v178
	v_cvt_f32_ubyte0_e32 v189, v177
	v_rcp_f32_e32 v176, v186
	s_nop 0
	v_mul_f32_e32 v183, v182, v176
	v_cvt_f32_ubyte2_e32 v187, v177
	v_rcp_f32_e32 v176, v185
	s_nop 0
	v_mul_f32_e32 v182, v1, v176
	v_cvt_f32_ubyte2_e32 v1, v179
	v_cvt_f32_ubyte3_e32 v178, v179
	v_cvt_f32_ubyte0_e32 v176, v179
	v_cvt_f32_ubyte1_e32 v179, v179
	v_cvt_f32_ubyte1_e32 v184, v177
	v_cvt_f32_ubyte3_e32 v188, v177
	v_pk_mul_f32 v[96:97], v[96:97], v[180:181]
	v_pk_mul_f32 v[98:99], v[98:99], v[182:183]
	v_rcp_f32_e32 v177, v184
	s_nop 0
	v_mul_f32_e32 v177, v179, v177
	s_waitcnt vmcnt(5)
	v_cvt_f32_ubyte2_e32 v181, v172
	v_rcp_f32_e32 v179, v189
	s_nop 0
	v_mul_f32_e32 v176, v176, v179
	v_pk_mul_f32 v[92:93], v[92:93], v[176:177]
	v_rcp_f32_e32 v179, v188
	s_nop 0
	v_mul_f32_e32 v179, v178, v179
	s_waitcnt vmcnt(4)
	v_cvt_f32_ubyte0_e32 v176, v174
	v_rcp_f32_e32 v178, v187
	s_nop 0
	v_mul_f32_e32 v178, v1, v178
	v_pk_mul_f32 v[94:95], v[94:95], v[178:179]
	v_cvt_f32_ubyte2_e32 v1, v174
	v_cvt_f32_ubyte3_e32 v178, v174
	v_cvt_f32_ubyte1_e32 v174, v174
	v_cvt_f32_ubyte1_e32 v177, v172
	v_cvt_f32_ubyte3_e32 v182, v172
	v_cvt_f32_ubyte0_e32 v172, v172
	v_rcp_f32_e32 v179, v177
	s_nop 0
	v_mul_f32_e32 v177, v174, v179
	v_rcp_f32_e32 v174, v172
	s_nop 0
	v_mul_f32_e32 v176, v176, v174
	v_cvt_f32_ubyte0_e32 v185, v173
	v_rcp_f32_e32 v172, v182
	s_nop 0
	v_mul_f32_e32 v179, v178, v172
	v_cvt_f32_ubyte2_e32 v183, v173
	v_rcp_f32_e32 v172, v181
	s_nop 0
	v_mul_f32_e32 v178, v1, v172
	v_cvt_f32_ubyte2_e32 v1, v175
	v_cvt_f32_ubyte3_e32 v174, v175
	v_cvt_f32_ubyte0_e32 v172, v175
	v_cvt_f32_ubyte1_e32 v175, v175
	v_cvt_f32_ubyte1_e32 v180, v173
	v_cvt_f32_ubyte3_e32 v184, v173
	v_pk_mul_f32 v[88:89], v[88:89], v[176:177]
	v_pk_mul_f32 v[90:91], v[90:91], v[178:179]
	v_rcp_f32_e32 v173, v180
	s_nop 0
	v_mul_f32_e32 v173, v175, v173
	s_waitcnt vmcnt(2)
	v_cvt_f32_ubyte2_e32 v177, v168
	v_rcp_f32_e32 v175, v185
	s_nop 0
	v_mul_f32_e32 v172, v172, v175
	v_pk_mul_f32 v[84:85], v[84:85], v[172:173]
	v_rcp_f32_e32 v175, v184
	s_nop 0
	v_mul_f32_e32 v175, v174, v175
	v_cvt_f32_ubyte0_e32 v172, v170
	v_rcp_f32_e32 v174, v183
	s_nop 0
	v_mul_f32_e32 v174, v1, v174
	v_pk_mul_f32 v[86:87], v[86:87], v[174:175]
	v_cvt_f32_ubyte2_e32 v1, v170
	v_cvt_f32_ubyte3_e32 v174, v170
	v_cvt_f32_ubyte1_e32 v170, v170
	v_cvt_f32_ubyte1_e32 v173, v168
	v_cvt_f32_ubyte3_e32 v178, v168
	v_cvt_f32_ubyte0_e32 v168, v168
	v_rcp_f32_e32 v175, v173
	s_nop 0
	v_mul_f32_e32 v173, v170, v175
	v_rcp_f32_e32 v170, v168
	s_nop 0
	v_mul_f32_e32 v172, v172, v170
	v_cvt_f32_ubyte0_e32 v181, v169
	v_rcp_f32_e32 v168, v178
	s_nop 0
	v_mul_f32_e32 v175, v174, v168
	v_cvt_f32_ubyte2_e32 v179, v169
	v_rcp_f32_e32 v168, v177
	s_nop 0
	v_mul_f32_e32 v174, v1, v168
	v_cvt_f32_ubyte2_e32 v1, v171
	v_cvt_f32_ubyte3_e32 v170, v171
	v_cvt_f32_ubyte0_e32 v168, v171
	v_cvt_f32_ubyte1_e32 v171, v171
	v_cvt_f32_ubyte1_e32 v176, v169
	v_cvt_f32_ubyte3_e32 v180, v169
	v_pk_mul_f32 v[80:81], v[80:81], v[172:173]
	v_pk_mul_f32 v[82:83], v[82:83], v[174:175]
	v_rcp_f32_e32 v169, v176
	s_nop 0
	v_mul_f32_e32 v169, v171, v169
	s_waitcnt vmcnt(1)
	v_cvt_f32_ubyte2_e32 v173, v164
	v_rcp_f32_e32 v171, v181
	s_nop 0
	v_mul_f32_e32 v168, v168, v171
	v_pk_mul_f32 v[76:77], v[76:77], v[168:169]
	v_rcp_f32_e32 v171, v180
	s_nop 0
	v_mul_f32_e32 v171, v170, v171
	s_waitcnt vmcnt(0)
	v_cvt_f32_ubyte0_e32 v168, v166
	v_rcp_f32_e32 v170, v179
	s_nop 0
	v_mul_f32_e32 v170, v1, v170
	v_pk_mul_f32 v[78:79], v[78:79], v[170:171]
	v_cvt_f32_ubyte2_e32 v1, v166
	v_cvt_f32_ubyte3_e32 v170, v166
	v_cvt_f32_ubyte1_e32 v166, v166
	v_cvt_f32_ubyte1_e32 v169, v164
	v_cvt_f32_ubyte3_e32 v174, v164
	v_cvt_f32_ubyte0_e32 v164, v164
	v_cvt_f32_ubyte0_e32 v178, v165
	v_rcp_f32_e32 v171, v169
	s_nop 0
	v_mul_f32_e32 v169, v166, v171
	v_rcp_f32_e32 v166, v164
	s_nop 0
	v_mul_f32_e32 v168, v168, v166
	v_cvt_f32_ubyte3_e32 v177, v165
	v_rcp_f32_e32 v164, v174
	s_nop 0
	v_mul_f32_e32 v171, v170, v164
	v_pk_mul_f32 v[72:73], v[72:73], v[168:169]
	v_rcp_f32_e32 v164, v173
	s_nop 0
	v_mul_f32_e32 v170, v1, v164
	v_cvt_f32_ubyte2_e32 v1, v167
	v_cvt_f32_ubyte3_e32 v172, v167
	v_cvt_f32_ubyte0_e32 v166, v167
	v_cvt_f32_ubyte1_e32 v167, v167
	v_cvt_f32_ubyte1_e32 v173, v165
	v_cvt_f32_ubyte2_e32 v176, v165
	v_add_co_u32_e64 v164, s[4:5], s59, v2
	s_nop 0
	v_addc_co_u32_e64 v165, s[4:5], 0, v3, s[4:5]
	global_load_dwordx2 v[190:191], v[164:165], off
	global_load_dwordx2 v[198:199], v[164:165], off offset:2048
	v_rcp_f32_e32 v174, v173
	s_nop 0
	v_mul_f32_e32 v167, v167, v174
	global_load_dwordx2 v[186:187], v[164:165], off offset:2176
	global_load_dwordx2 v[188:189], v[164:165], off offset:128
	v_rcp_f32_e32 v173, v178
	s_nop 0
	v_mul_f32_e32 v166, v166, v173
	v_pk_mul_f32 v[74:75], v[74:75], v[170:171]
	v_rcp_f32_e32 v173, v177
	s_nop 0
	v_mul_f32_e32 v173, v172, v173
	v_pk_mul_f32 v[68:69], v[68:69], v[166:167]
	v_rcp_f32_e32 v172, v176
	s_nop 0
	v_mul_f32_e32 v172, v1, v172
	v_add_co_u32_e32 v164, vcc, s60, v2
	v_pk_mul_f32 v[70:71], v[70:71], v[172:173]
	s_nop 0
	v_addc_co_u32_e32 v165, vcc, 0, v3, vcc
	global_load_dwordx2 v[184:185], v[164:165], off
	global_load_dwordx2 v[182:183], v[164:165], off offset:2048
	global_load_dwordx2 v[178:179], v[164:165], off offset:2176
	global_load_dwordx2 v[180:181], v[164:165], off offset:128
	v_add_co_u32_e32 v164, vcc, s61, v2
	s_waitcnt vmcnt(7)
; __device__ __forceinline__ float ub0(unsigned w) { return (float)(w & 0xffu); }
; __device__ __forceinline__ float ub1(unsigned w) { return (float)((w >> 8) & 0xffu); }
; __device__ __forceinline__ float ub2(unsigned w) { return (float)((w >> 16) & 0xffu); }
; __device__ __forceinline__ float ub3(unsigned w) { return (float)(w >> 24); }
;     __device__ __forceinline__ void mid(f32x4 (&acc)[2][2][4][2], const Unit& u, int wr, int wc, int fr, int fq, int t) const {
;     ...
;                 for (int bj = 0; bj < 2; ++bj) { const unsigned char* gp = gp0 + (size_t)(ai * HALF + m * 16) * GP8 + bj * HALF; gx[m][bj] = *(const u32x2*)gp; gy[m][bj] = *(const u32x2*)(gp + 2048); }
; #pragma unroll
;             for (int m = 0; m < 4; ++m)
; #pragma unroll
;                 for (int bj = 0; bj < 2; ++bj) { const u32x2 x = gx[m][bj], y = gy[m][bj];
;                     f32x4 r0, r1;
;                     r0[0] = __fdividef(ub0(x.x), ub0(y.x)); r0[1] = __fdividef(ub1(x.x), ub1(y.x)); r0[2] = __fdividef(ub2(x.x), ub2(y.x)); r0[3] = __fdividef(ub3(x.x), ub3(y.x));
;                     r1[0] = __fdividef(ub0(x.y), ub0(y.y)); r1[1] = __fdividef(ub1(x.y), ub1(y.y)); r1[2] = __fdividef(ub2(x.y), ub2(y.y)); r1[3] = __fdividef(ub3(x.y), ub3(y.y));
;                     acc[ai][bj][m][0] *= r0; acc[ai][bj][m][1] *= r1; }
	v_cvt_f32_ubyte2_e32 v1, v190
	v_cvt_f32_ubyte3_e32 v202, v190
	v_cvt_f32_ubyte0_e32 v200, v190
	v_cvt_f32_ubyte1_e32 v190, v190
	s_waitcnt vmcnt(6)
	v_cvt_f32_ubyte1_e32 v201, v198
	v_addc_co_u32_e32 v165, vcc, 0, v3, vcc
	global_load_dwordx2 v[176:177], v[164:165], off
	global_load_dwordx2 v[174:175], v[164:165], off offset:2048
	global_load_dwordx2 v[170:171], v[164:165], off offset:2176
	global_load_dwordx2 v[172:173], v[164:165], off offset:128
	v_add_co_u32_e32 v164, vcc, s62, v2
	s_nop 0
	v_addc_co_u32_e32 v165, vcc, 0, v3, vcc
	v_cvt_f32_ubyte2_e32 v205, v198
	v_cvt_f32_ubyte3_e32 v206, v198
	v_cvt_f32_ubyte0_e32 v198, v198
	v_rcp_f32_e32 v203, v201
	s_nop 0
	v_mul_f32_e32 v201, v190, v203
	global_load_dwordx2 v[168:169], v[164:165], off
	global_load_dwordx2 v[166:167], v[164:165], off offset:2048
	global_load_dwordx2 v[2:3], v[164:165], off offset:2176
	s_nop 0
	global_load_dwordx2 v[164:165], v[164:165], off offset:128
	v_rcp_f32_e32 v190, v198
	s_nop 0
	v_mul_f32_e32 v200, v200, v190
	v_pk_mul_f32 v[64:65], v[64:65], v[200:201]
	v_rcp_f32_e32 v190, v206
	s_nop 0
	v_mul_f32_e32 v203, v202, v190
	v_cvt_f32_ubyte2_e32 v207, v199
	v_rcp_f32_e32 v190, v205
	s_nop 0
	v_mul_f32_e32 v202, v1, v190
	v_cvt_f32_ubyte2_e32 v1, v191
	v_cvt_f32_ubyte3_e32 v198, v191
	v_cvt_f32_ubyte0_e32 v190, v191
	v_cvt_f32_ubyte1_e32 v191, v191
	v_cvt_f32_ubyte1_e32 v204, v199
	v_cvt_f32_ubyte3_e32 v208, v199
	v_cvt_f32_ubyte0_e32 v199, v199
	v_pk_mul_f32 v[66:67], v[66:67], v[202:203]
	v_rcp_f32_e32 v205, v204
	s_nop 0
	v_mul_f32_e32 v191, v191, v205
	s_waitcnt vmcnt(13)
	v_cvt_f32_ubyte2_e32 v201, v186
	v_rcp_f32_e32 v204, v199
	s_nop 0
	v_mul_f32_e32 v190, v190, v204
	v_pk_mul_f32 v[60:61], v[60:61], v[190:191]
	v_rcp_f32_e32 v199, v208
	s_nop 0
	v_mul_f32_e32 v199, v198, v199
	s_waitcnt vmcnt(12)
	v_cvt_f32_ubyte0_e32 v190, v188
	v_rcp_f32_e32 v198, v207
	s_nop 0
	v_mul_f32_e32 v198, v1, v198
	v_pk_mul_f32 v[62:63], v[62:63], v[198:199]
	v_cvt_f32_ubyte2_e32 v1, v188
	v_cvt_f32_ubyte3_e32 v198, v188
	v_cvt_f32_ubyte1_e32 v188, v188
	v_cvt_f32_ubyte1_e32 v191, v186
	v_cvt_f32_ubyte3_e32 v202, v186
	v_cvt_f32_ubyte0_e32 v186, v186
	v_rcp_f32_e32 v199, v191
	s_nop 0
	v_mul_f32_e32 v191, v188, v199
	v_rcp_f32_e32 v188, v186
	s_nop 0
	v_mul_f32_e32 v190, v190, v188
	v_cvt_f32_ubyte0_e32 v205, v187
	v_rcp_f32_e32 v186, v202
	s_nop 0
	v_mul_f32_e32 v199, v198, v186
	v_cvt_f32_ubyte2_e32 v203, v187
	v_rcp_f32_e32 v186, v201
	s_nop 0
	v_mul_f32_e32 v198, v1, v186
	v_cvt_f32_ubyte2_e32 v1, v189
	v_cvt_f32_ubyte3_e32 v188, v189
	v_cvt_f32_ubyte0_e32 v186, v189
	v_cvt_f32_ubyte1_e32 v189, v189
	v_cvt_f32_ubyte1_e32 v200, v187
	v_cvt_f32_ubyte3_e32 v204, v187
	v_pk_mul_f32 v[56:57], v[56:57], v[190:191]
	v_pk_mul_f32 v[58:59], v[58:59], v[198:199]
	v_rcp_f32_e32 v187, v200
	s_nop 0
	v_mul_f32_e32 v187, v189, v187
	s_waitcnt vmcnt(10)
	v_cvt_f32_ubyte2_e32 v191, v182
	v_rcp_f32_e32 v189, v205
	s_nop 0
	v_mul_f32_e32 v186, v186, v189
	v_pk_mul_f32 v[52:53], v[52:53], v[186:187]
	v_rcp_f32_e32 v189, v204
	s_nop 0
	v_mul_f32_e32 v189, v188, v189
	v_cvt_f32_ubyte0_e32 v186, v184
	v_rcp_f32_e32 v188, v203
	s_nop 0
	v_mul_f32_e32 v188, v1, v188
	v_pk_mul_f32 v[54:55], v[54:55], v[188:189]
	v_cvt_f32_ubyte2_e32 v1, v184
	v_cvt_f32_ubyte3_e32 v188, v184
	v_cvt_f32_ubyte1_e32 v184, v184
	v_cvt_f32_ubyte1_e32 v187, v182
	v_cvt_f32_ubyte3_e32 v198, v182
	v_cvt_f32_ubyte0_e32 v182, v182
	v_rcp_f32_e32 v189, v187
	s_nop 0
	v_mul_f32_e32 v187, v184, v189
	v_rcp_f32_e32 v184, v182
	s_nop 0
	v_mul_f32_e32 v186, v186, v184
	v_cvt_f32_ubyte0_e32 v201, v183
	v_rcp_f32_e32 v182, v198
	s_nop 0
	v_mul_f32_e32 v189, v188, v182
	v_cvt_f32_ubyte2_e32 v199, v183
	v_rcp_f32_e32 v182, v191
	s_nop 0
	v_mul_f32_e32 v188, v1, v182
	v_cvt_f32_ubyte2_e32 v1, v185
	v_cvt_f32_ubyte3_e32 v184, v185
	v_cvt_f32_ubyte0_e32 v182, v185
	v_cvt_f32_ubyte1_e32 v185, v185
	v_cvt_f32_ubyte1_e32 v190, v183
	v_cvt_f32_ubyte3_e32 v200, v183
	v_pk_mul_f32 v[48:49], v[48:49], v[186:187]
	v_pk_mul_f32 v[50:51], v[50:51], v[188:189]
	v_rcp_f32_e32 v183, v190
	s_nop 0
	v_mul_f32_e32 v183, v185, v183
	s_waitcnt vmcnt(9)
	v_cvt_f32_ubyte2_e32 v187, v178
	v_rcp_f32_e32 v185, v201
	s_nop 0
	v_mul_f32_e32 v182, v182, v185
	v_pk_mul_f32 v[44:45], v[44:45], v[182:183]
	v_rcp_f32_e32 v185, v200
	s_nop 0
	v_mul_f32_e32 v185, v184, v185
	s_waitcnt vmcnt(8)
	v_cvt_f32_ubyte0_e32 v182, v180
	v_rcp_f32_e32 v184, v199
	s_nop 0
	v_mul_f32_e32 v184, v1, v184
	v_pk_mul_f32 v[46:47], v[46:47], v[184:185]
	v_cvt_f32_ubyte2_e32 v1, v180
	v_cvt_f32_ubyte3_e32 v184, v180
	v_cvt_f32_ubyte1_e32 v180, v180
	v_cvt_f32_ubyte1_e32 v183, v178
	v_cvt_f32_ubyte3_e32 v188, v178
	v_cvt_f32_ubyte0_e32 v178, v178
	v_rcp_f32_e32 v185, v183
	s_nop 0
	v_mul_f32_e32 v183, v180, v185
	v_rcp_f32_e32 v180, v178
	s_nop 0
	v_mul_f32_e32 v182, v182, v180
	v_cvt_f32_ubyte0_e32 v191, v179
	v_rcp_f32_e32 v178, v188
	s_nop 0
	v_mul_f32_e32 v185, v184, v178
	v_cvt_f32_ubyte2_e32 v189, v179
	v_rcp_f32_e32 v178, v187
	s_nop 0
	v_mul_f32_e32 v184, v1, v178
	v_cvt_f32_ubyte2_e32 v1, v181
	v_cvt_f32_ubyte3_e32 v180, v181
	v_cvt_f32_ubyte0_e32 v178, v181
	v_cvt_f32_ubyte1_e32 v181, v181
	v_cvt_f32_ubyte1_e32 v186, v179
	v_cvt_f32_ubyte3_e32 v190, v179
	v_pk_mul_f32 v[40:41], v[40:41], v[182:183]
	v_pk_mul_f32 v[42:43], v[42:43], v[184:185]
	v_rcp_f32_e32 v179, v186
	s_nop 0
	v_mul_f32_e32 v179, v181, v179
	s_waitcnt vmcnt(6)
; __device__ __forceinline__ float ub0(unsigned w) { return (float)(w & 0xffu); }
; __device__ __forceinline__ float ub1(unsigned w) { return (float)((w >> 8) & 0xffu); }
; __device__ __forceinline__ float ub2(unsigned w) { return (float)((w >> 16) & 0xffu); }
; __device__ __forceinline__ float ub3(unsigned w) { return (float)(w >> 24); }
;     __device__ __forceinline__ void mid(f32x4 (&acc)[2][2][4][2], const Unit& u, int wr, int wc, int fr, int fq, int t) const {
;     ...
;                 for (int bj = 0; bj < 2; ++bj) { const unsigned char* gp = gp0 + (size_t)(ai * HALF + m * 16) * GP8 + bj * HALF; gx[m][bj] = *(const u32x2*)gp; gy[m][bj] = *(const u32x2*)(gp + 2048); }
; #pragma unroll
;             for (int m = 0; m < 4; ++m)
; #pragma unroll
;                 for (int bj = 0; bj < 2; ++bj) { const u32x2 x = gx[m][bj], y = gy[m][bj];
;                     f32x4 r0, r1;
;                     r0[0] = __fdividef(ub0(x.x), ub0(y.x)); r0[1] = __fdividef(ub1(x.x), ub1(y.x)); r0[2] = __fdividef(ub2(x.x), ub2(y.x)); r0[3] = __fdividef(ub3(x.x), ub3(y.x));
;                     r1[0] = __fdividef(ub0(x.y), ub0(y.y)); r1[1] = __fdividef(ub1(x.y), ub1(y.y)); r1[2] = __fdividef(ub2(x.y), ub2(y.y)); r1[3] = __fdividef(ub3(x.y), ub3(y.y));
;                     acc[ai][bj][m][0] *= r0; acc[ai][bj][m][1] *= r1; }
;             asm volatile("" ::: "memory"); }
	v_cvt_f32_ubyte2_e32 v183, v174
	v_rcp_f32_e32 v181, v191
	s_nop 0
	v_mul_f32_e32 v178, v178, v181
	v_pk_mul_f32 v[36:37], v[36:37], v[178:179]
	v_rcp_f32_e32 v181, v190
	s_nop 0
	v_mul_f32_e32 v181, v180, v181
	v_cvt_f32_ubyte0_e32 v178, v176
	v_rcp_f32_e32 v180, v189
	s_nop 0
	v_mul_f32_e32 v180, v1, v180
	v_pk_mul_f32 v[38:39], v[38:39], v[180:181]
	v_cvt_f32_ubyte2_e32 v1, v176
	v_cvt_f32_ubyte3_e32 v180, v176
	v_cvt_f32_ubyte1_e32 v176, v176
	v_cvt_f32_ubyte1_e32 v179, v174
	v_cvt_f32_ubyte3_e32 v184, v174
	v_cvt_f32_ubyte0_e32 v174, v174
	v_rcp_f32_e32 v181, v179
	s_nop 0
	v_mul_f32_e32 v179, v176, v181
	v_rcp_f32_e32 v176, v174
	s_nop 0
	v_mul_f32_e32 v178, v178, v176
	v_cvt_f32_ubyte0_e32 v187, v175
	v_rcp_f32_e32 v174, v184
	s_nop 0
	v_mul_f32_e32 v181, v180, v174
	v_cvt_f32_ubyte2_e32 v185, v175
	v_rcp_f32_e32 v174, v183
	s_nop 0
	v_mul_f32_e32 v180, v1, v174
	v_cvt_f32_ubyte2_e32 v1, v177
	v_cvt_f32_ubyte3_e32 v176, v177
	v_cvt_f32_ubyte0_e32 v174, v177
	v_cvt_f32_ubyte1_e32 v177, v177
	v_cvt_f32_ubyte1_e32 v182, v175
	v_cvt_f32_ubyte3_e32 v186, v175
	v_pk_mul_f32 v[32:33], v[32:33], v[178:179]
	v_pk_mul_f32 v[34:35], v[34:35], v[180:181]
	v_rcp_f32_e32 v175, v182
	s_nop 0
	v_mul_f32_e32 v175, v177, v175
	s_waitcnt vmcnt(5)
	v_cvt_f32_ubyte2_e32 v179, v170
	v_rcp_f32_e32 v177, v187
	s_nop 0
	v_mul_f32_e32 v174, v174, v177
	v_pk_mul_f32 v[28:29], v[28:29], v[174:175]
	v_rcp_f32_e32 v177, v186
	s_nop 0
	v_mul_f32_e32 v177, v176, v177
	s_waitcnt vmcnt(4)
	v_cvt_f32_ubyte0_e32 v174, v172
	v_rcp_f32_e32 v176, v185
	s_nop 0
	v_mul_f32_e32 v176, v1, v176
	v_pk_mul_f32 v[30:31], v[30:31], v[176:177]
	v_cvt_f32_ubyte2_e32 v1, v172
	v_cvt_f32_ubyte3_e32 v176, v172
	v_cvt_f32_ubyte1_e32 v172, v172
	v_cvt_f32_ubyte1_e32 v175, v170
	v_cvt_f32_ubyte3_e32 v180, v170
	v_cvt_f32_ubyte0_e32 v170, v170
	v_rcp_f32_e32 v177, v175
	s_nop 0
	v_mul_f32_e32 v175, v172, v177
	v_rcp_f32_e32 v172, v170
	s_nop 0
	v_mul_f32_e32 v174, v174, v172
	v_cvt_f32_ubyte0_e32 v183, v171
	v_rcp_f32_e32 v170, v180
	s_nop 0
	v_mul_f32_e32 v177, v176, v170
	v_cvt_f32_ubyte2_e32 v181, v171
	v_rcp_f32_e32 v170, v179
	s_nop 0
	v_mul_f32_e32 v176, v1, v170
	v_cvt_f32_ubyte2_e32 v1, v173
	v_cvt_f32_ubyte3_e32 v172, v173
	v_cvt_f32_ubyte0_e32 v170, v173
	v_cvt_f32_ubyte1_e32 v173, v173
	v_cvt_f32_ubyte1_e32 v178, v171
	v_cvt_f32_ubyte3_e32 v182, v171
	v_pk_mul_f32 v[24:25], v[24:25], v[174:175]
	v_pk_mul_f32 v[26:27], v[26:27], v[176:177]
	v_rcp_f32_e32 v171, v178
	s_nop 0
	v_mul_f32_e32 v171, v173, v171
	s_waitcnt vmcnt(2)
	v_cvt_f32_ubyte2_e32 v175, v166
	v_rcp_f32_e32 v173, v183
	s_nop 0
	v_mul_f32_e32 v170, v170, v173
	v_pk_mul_f32 v[20:21], v[20:21], v[170:171]
	v_rcp_f32_e32 v173, v182
	s_nop 0
	v_mul_f32_e32 v173, v172, v173
	v_cvt_f32_ubyte0_e32 v170, v168
	v_rcp_f32_e32 v172, v181
	s_nop 0
	v_mul_f32_e32 v172, v1, v172
	v_pk_mul_f32 v[22:23], v[22:23], v[172:173]
	v_cvt_f32_ubyte2_e32 v1, v168
	v_cvt_f32_ubyte3_e32 v172, v168
	v_cvt_f32_ubyte1_e32 v168, v168
	v_cvt_f32_ubyte1_e32 v171, v166
	v_cvt_f32_ubyte3_e32 v176, v166
	v_cvt_f32_ubyte0_e32 v166, v166
	v_rcp_f32_e32 v173, v171
	s_nop 0
	v_mul_f32_e32 v171, v168, v173
	v_rcp_f32_e32 v168, v166
	s_nop 0
	v_mul_f32_e32 v170, v170, v168
	v_cvt_f32_ubyte0_e32 v179, v167
	v_rcp_f32_e32 v166, v176
	s_nop 0
	v_mul_f32_e32 v173, v172, v166
	v_cvt_f32_ubyte2_e32 v177, v167
	v_rcp_f32_e32 v166, v175
	s_nop 0
	v_mul_f32_e32 v172, v1, v166
	v_cvt_f32_ubyte2_e32 v1, v169
	v_cvt_f32_ubyte3_e32 v168, v169
	v_cvt_f32_ubyte0_e32 v166, v169
	v_cvt_f32_ubyte1_e32 v169, v169
	v_cvt_f32_ubyte1_e32 v174, v167
	v_cvt_f32_ubyte3_e32 v178, v167
	v_pk_mul_f32 v[16:17], v[16:17], v[170:171]
	v_pk_mul_f32 v[18:19], v[18:19], v[172:173]
	v_rcp_f32_e32 v167, v174
	s_nop 0
	v_mul_f32_e32 v167, v169, v167
	s_waitcnt vmcnt(1)
	v_cvt_f32_ubyte2_e32 v171, v2
	v_rcp_f32_e32 v169, v179
	s_nop 0
	v_mul_f32_e32 v166, v166, v169
	v_pk_mul_f32 v[12:13], v[12:13], v[166:167]
	v_rcp_f32_e32 v169, v178
	s_nop 0
	v_mul_f32_e32 v169, v168, v169
	s_waitcnt vmcnt(0)
	v_cvt_f32_ubyte0_e32 v166, v164
	v_rcp_f32_e32 v168, v177
	s_nop 0
	v_mul_f32_e32 v168, v1, v168
	v_pk_mul_f32 v[14:15], v[14:15], v[168:169]
	v_cvt_f32_ubyte2_e32 v1, v164
	v_cvt_f32_ubyte3_e32 v168, v164
	v_cvt_f32_ubyte1_e32 v164, v164
	v_cvt_f32_ubyte1_e32 v167, v2
	v_cvt_f32_ubyte3_e32 v172, v2
	v_cvt_f32_ubyte0_e32 v2, v2
	v_rcp_f32_e32 v169, v167
	s_nop 0
	v_mul_f32_e32 v167, v164, v169
	v_rcp_f32_e32 v164, v2
	s_nop 0
	v_mul_f32_e32 v166, v166, v164
	v_cvt_f32_ubyte0_e32 v175, v3
	v_rcp_f32_e32 v2, v172
	s_nop 0
	v_mul_f32_e32 v169, v168, v2
	v_cvt_f32_ubyte2_e32 v173, v3
	v_rcp_f32_e32 v2, v171
	s_nop 0
	v_mul_f32_e32 v168, v1, v2
	v_cvt_f32_ubyte2_e32 v1, v165
	v_cvt_f32_ubyte3_e32 v164, v165
	v_cvt_f32_ubyte0_e32 v2, v165
	v_cvt_f32_ubyte1_e32 v165, v165
	v_cvt_f32_ubyte1_e32 v170, v3
	v_cvt_f32_ubyte3_e32 v174, v3
	v_pk_mul_f32 v[10:11], v[10:11], v[168:169]
	v_pk_mul_f32 v[8:9], v[8:9], v[166:167]
	v_rcp_f32_e32 v3, v170
	s_nop 0
	v_mul_f32_e32 v3, v165, v3
	v_rcp_f32_e32 v165, v175
	s_nop 0
	v_mul_f32_e32 v2, v2, v165
	v_pk_mul_f32 v[4:5], v[4:5], v[2:3]
	v_rcp_f32_e32 v165, v174
	s_nop 0
	v_mul_f32_e32 v165, v164, v165
	v_rcp_f32_e32 v164, v173
	s_nop 0
	v_mul_f32_e32 v164, v1, v164
	v_pk_mul_f32 v[6:7], v[6:7], v[164:165]
